# v6 + relaxed post-epilogue K-loop waits + attention K/V DMA issued at step start + static prio for waves 4-7 in attention/S5 + P0 x->bf16 4x unroll
# baseline (speedup 1.0000x reference)
.Lwd_0_0:
	s_waitcnt lgkmcnt(0)
	s_barrier
	s_waitcnt lgkmcnt(7)
	v_mfma_f32_16x16x32_bf16 v[122:125], v[140:143], v[172:175], v[122:125]
	v_mfma_f32_16x16x32_bf16 v[114:117], v[148:151], v[172:175], v[114:117]
	s_waitcnt lgkmcnt(5)
	v_mfma_f32_16x16x32_bf16 v[106:109], v[140:143], v[180:183], v[106:109]
	v_mfma_f32_16x16x32_bf16 v[98:101], v[148:151], v[180:183], v[98:101]
	s_waitcnt lgkmcnt(3)
	v_mfma_f32_16x16x32_bf16 v[90:93], v[140:143], v[188:191], v[90:93]
	v_mfma_f32_16x16x32_bf16 v[82:85], v[148:151], v[188:191], v[82:85]
	s_waitcnt lgkmcnt(1)
	v_mfma_f32_16x16x32_bf16 v[74:77], v[140:143], v[196:199], v[74:77]
	v_mfma_f32_16x16x32_bf16 v[66:69], v[148:151], v[196:199], v[66:69]
	v_mfma_f32_16x16x32_bf16 v[122:125], v[144:147], v[176:179], v[122:125]
	v_mfma_f32_16x16x32_bf16 v[114:117], v[152:155], v[176:179], v[114:117]
	v_mfma_f32_16x16x32_bf16 v[106:109], v[144:147], v[184:187], v[106:109]
	v_mfma_f32_16x16x32_bf16 v[98:101], v[152:155], v[184:187], v[98:101]
	v_mfma_f32_16x16x32_bf16 v[90:93], v[144:147], v[192:195], v[90:93]
	v_mfma_f32_16x16x32_bf16 v[82:85], v[152:155], v[192:195], v[82:85]
	s_waitcnt lgkmcnt(0)
	v_mfma_f32_16x16x32_bf16 v[74:77], v[144:147], v[200:203], v[74:77]
	v_mfma_f32_16x16x32_bf16 v[66:69], v[152:155], v[200:203], v[66:69]
	v_mfma_f32_16x16x32_bf16 v[126:129], v[156:159], v[172:175], v[126:129]
	v_mfma_f32_16x16x32_bf16 v[118:121], v[164:167], v[172:175], v[118:121]
	v_mfma_f32_16x16x32_bf16 v[110:113], v[156:159], v[180:183], v[110:113]
	v_mfma_f32_16x16x32_bf16 v[102:105], v[164:167], v[180:183], v[102:105]
	v_mfma_f32_16x16x32_bf16 v[94:97], v[156:159], v[188:191], v[94:97]
	v_mfma_f32_16x16x32_bf16 v[86:89], v[164:167], v[188:191], v[86:89]
	v_mfma_f32_16x16x32_bf16 v[78:81], v[156:159], v[196:199], v[78:81]
	v_mfma_f32_16x16x32_bf16 v[70:73], v[164:167], v[196:199], v[70:73]
	v_mfma_f32_16x16x32_bf16 v[126:129], v[160:163], v[176:179], v[126:129]
	v_mfma_f32_16x16x32_bf16 v[118:121], v[168:171], v[176:179], v[118:121]
	v_mfma_f32_16x16x32_bf16 v[110:113], v[160:163], v[184:187], v[110:113]
	v_mfma_f32_16x16x32_bf16 v[102:105], v[168:171], v[184:187], v[102:105]
	v_mfma_f32_16x16x32_bf16 v[94:97], v[160:163], v[192:195], v[94:97]
	v_mfma_f32_16x16x32_bf16 v[86:89], v[168:171], v[192:195], v[86:89]
	v_mfma_f32_16x16x32_bf16 v[78:81], v[160:163], v[200:203], v[78:81]
	v_mfma_f32_16x16x32_bf16 v[70:73], v[168:171], v[200:203], v[70:73]
	s_barrier
	s_add_u32 s52, s56, 0x20000
	ds_read_b128 v[172:175], v138 offset:16384
	ds_read_b128 v[176:179], v138 offset:17408
	ds_read_b128 v[180:183], v138 offset:18432
	ds_read_b128 v[184:187], v138 offset:19456
	ds_read_b128 v[188:191], v138 offset:20480
	ds_read_b128 v[192:195], v138 offset:21504
	ds_read_b128 v[196:199], v138 offset:22528
	ds_read_b128 v[200:203], v138 offset:23552
	s_mov_b32 s12, m0
	s_mov_b32 m0, s62
	s_nop 4
	global_load_lds_dwordx4 v134, s[56:57]
	s_mov_b32 m0, s12
	s_addc_u32 s53, s57, 0
	s_mov_b32 s12, m0
	s_mov_b32 m0, s63
	s_nop 4
	global_load_lds_dwordx4 v134, s[52:53]
	s_mov_b32 m0, s12
	s_add_u32 s52, s56, 0x40000
	s_addc_u32 s53, s57, 0
	s_mov_b32 s12, m0
	s_mov_b32 m0, s64
	s_nop 4
	global_load_lds_dwordx4 v134, s[52:53]
	s_mov_b32 m0, s12
	s_add_u32 s52, s56, 0x60000
	s_addc_u32 s53, s57, 0
	s_mov_b32 s12, m0
	s_mov_b32 m0, s65
	s_nop 4
	global_load_lds_dwordx4 v134, s[52:53]
	s_mov_b32 m0, s12
	s_add_u32 s52, s34, 0x20000
	s_mov_b32 s12, m0
	s_mov_b32 m0, s51
	s_nop 4
	global_load_lds_dwordx4 v1, s[34:35]
	s_mov_b32 m0, s12
	s_addc_u32 s53, s35, 0
	s_mov_b32 s12, m0
	s_mov_b32 m0, s73
	s_nop 4
	global_load_lds_dwordx4 v1, s[52:53]
	s_mov_b32 m0, s12
	s_cmp_eq_u32 s89, -2
	s_cselect_b32 s99, s98, 0
	s_cmp_eq_u32 s99, 0
	s_cbranch_scc1 .Lw8_0_1
	s_waitcnt vmcnt(16)
	s_branch .Lwd_0_1

.Lwd_0_1:
	s_waitcnt lgkmcnt(0)
	s_barrier
	s_waitcnt lgkmcnt(7)
	v_mfma_f32_16x16x32_bf16 v[58:61], v[140:143], v[172:175], v[58:61]
	v_mfma_f32_16x16x32_bf16 v[50:53], v[148:151], v[172:175], v[50:53]
	s_waitcnt lgkmcnt(5)
	v_mfma_f32_16x16x32_bf16 v[42:45], v[140:143], v[180:183], v[42:45]
	v_mfma_f32_16x16x32_bf16 v[34:37], v[148:151], v[180:183], v[34:37]
	s_waitcnt lgkmcnt(3)
	v_mfma_f32_16x16x32_bf16 v[26:29], v[140:143], v[188:191], v[26:29]
	v_mfma_f32_16x16x32_bf16 v[18:21], v[148:151], v[188:191], v[18:21]
	s_waitcnt lgkmcnt(1)
	v_mfma_f32_16x16x32_bf16 v[10:13], v[140:143], v[196:199], v[10:13]
	v_mfma_f32_16x16x32_bf16 v[2:5], v[148:151], v[196:199], v[2:5]
	v_mfma_f32_16x16x32_bf16 v[58:61], v[144:147], v[176:179], v[58:61]
	v_mfma_f32_16x16x32_bf16 v[50:53], v[152:155], v[176:179], v[50:53]
	v_mfma_f32_16x16x32_bf16 v[42:45], v[144:147], v[184:187], v[42:45]
	v_mfma_f32_16x16x32_bf16 v[34:37], v[152:155], v[184:187], v[34:37]
	v_mfma_f32_16x16x32_bf16 v[26:29], v[144:147], v[192:195], v[26:29]
	v_mfma_f32_16x16x32_bf16 v[18:21], v[152:155], v[192:195], v[18:21]
	s_waitcnt lgkmcnt(0)
	v_mfma_f32_16x16x32_bf16 v[10:13], v[144:147], v[200:203], v[10:13]
	v_mfma_f32_16x16x32_bf16 v[2:5], v[152:155], v[200:203], v[2:5]
	v_mfma_f32_16x16x32_bf16 v[62:65], v[156:159], v[172:175], v[62:65]
	v_mfma_f32_16x16x32_bf16 v[54:57], v[164:167], v[172:175], v[54:57]
	v_mfma_f32_16x16x32_bf16 v[46:49], v[156:159], v[180:183], v[46:49]
	v_mfma_f32_16x16x32_bf16 v[38:41], v[164:167], v[180:183], v[38:41]
	v_mfma_f32_16x16x32_bf16 v[30:33], v[156:159], v[188:191], v[30:33]
	v_mfma_f32_16x16x32_bf16 v[22:25], v[164:167], v[188:191], v[22:25]
	v_mfma_f32_16x16x32_bf16 v[14:17], v[156:159], v[196:199], v[14:17]
	v_mfma_f32_16x16x32_bf16 v[6:9], v[164:167], v[196:199], v[6:9]
	v_mfma_f32_16x16x32_bf16 v[62:65], v[160:163], v[176:179], v[62:65]
	v_mfma_f32_16x16x32_bf16 v[54:57], v[168:171], v[176:179], v[54:57]
	v_mfma_f32_16x16x32_bf16 v[46:49], v[160:163], v[184:187], v[46:49]
	v_mfma_f32_16x16x32_bf16 v[38:41], v[168:171], v[184:187], v[38:41]
	v_mfma_f32_16x16x32_bf16 v[30:33], v[160:163], v[192:195], v[30:33]
	v_mfma_f32_16x16x32_bf16 v[22:25], v[168:171], v[192:195], v[22:25]
	v_mfma_f32_16x16x32_bf16 v[14:17], v[160:163], v[200:203], v[14:17]
	v_mfma_f32_16x16x32_bf16 v[6:9], v[168:171], v[200:203], v[6:9]
	s_barrier
	v_add_u32_e32 v139, 0x18000, v137
	ds_read_b128 v[140:143], v139
	ds_read_b128 v[144:147], v139 offset:1024
	ds_read_b128 v[148:151], v139 offset:2048
	ds_read_b128 v[152:155], v139 offset:3072
	v_add_u32_e32 v139, 0x1c000, v137
	ds_read_b128 v[156:159], v139
	ds_read_b128 v[160:163], v139 offset:1024
	ds_read_b128 v[164:167], v139 offset:2048
	ds_read_b128 v[168:171], v139 offset:3072
	ds_read_b128 v[172:175], v138 offset:32768
	ds_read_b128 v[176:179], v138 offset:33792
	ds_read_b128 v[180:183], v138 offset:34816
	ds_read_b128 v[184:187], v138 offset:35840
	ds_read_b128 v[188:191], v138 offset:36864
	ds_read_b128 v[192:195], v138 offset:37888
	ds_read_b128 v[196:199], v138 offset:38912
	ds_read_b128 v[200:203], v138 offset:39936
	s_add_u32 s52, s34, 0x40000
	s_addc_u32 s53, s35, 0
	s_mov_b32 s12, m0
	s_mov_b32 m0, s74
	s_nop 4
	global_load_lds_dwordx4 v1, s[52:53]
	s_mov_b32 m0, s12
	s_add_u32 s52, s34, 0x60000
	s_addc_u32 s53, s35, 0
	s_mov_b32 s12, m0
	s_mov_b32 m0, s75
	s_nop 4
	global_load_lds_dwordx4 v1, s[52:53]
	s_mov_b32 m0, s12
	s_waitcnt vmcnt(8)
	s_waitcnt lgkmcnt(0)
	s_barrier
	s_waitcnt lgkmcnt(7)
	v_mfma_f32_16x16x32_bf16 v[122:125], v[140:143], v[172:175], v[122:125]
	v_mfma_f32_16x16x32_bf16 v[114:117], v[148:151], v[172:175], v[114:117]
	s_waitcnt lgkmcnt(5)
	v_mfma_f32_16x16x32_bf16 v[106:109], v[140:143], v[180:183], v[106:109]
	v_mfma_f32_16x16x32_bf16 v[98:101], v[148:151], v[180:183], v[98:101]
	s_waitcnt lgkmcnt(3)
	v_mfma_f32_16x16x32_bf16 v[90:93], v[140:143], v[188:191], v[90:93]
	v_mfma_f32_16x16x32_bf16 v[82:85], v[148:151], v[188:191], v[82:85]
	s_waitcnt lgkmcnt(1)
	v_mfma_f32_16x16x32_bf16 v[74:77], v[140:143], v[196:199], v[74:77]
	v_mfma_f32_16x16x32_bf16 v[66:69], v[148:151], v[196:199], v[66:69]
	v_mfma_f32_16x16x32_bf16 v[122:125], v[144:147], v[176:179], v[122:125]
	v_mfma_f32_16x16x32_bf16 v[114:117], v[152:155], v[176:179], v[114:117]
	v_mfma_f32_16x16x32_bf16 v[106:109], v[144:147], v[184:187], v[106:109]
	v_mfma_f32_16x16x32_bf16 v[98:101], v[152:155], v[184:187], v[98:101]
	v_mfma_f32_16x16x32_bf16 v[90:93], v[144:147], v[192:195], v[90:93]
	v_mfma_f32_16x16x32_bf16 v[82:85], v[152:155], v[192:195], v[82:85]
	s_waitcnt lgkmcnt(0)
	v_mfma_f32_16x16x32_bf16 v[74:77], v[144:147], v[200:203], v[74:77]
	v_mfma_f32_16x16x32_bf16 v[66:69], v[152:155], v[200:203], v[66:69]
	v_mfma_f32_16x16x32_bf16 v[126:129], v[156:159], v[172:175], v[126:129]
	v_mfma_f32_16x16x32_bf16 v[118:121], v[164:167], v[172:175], v[118:121]
	v_mfma_f32_16x16x32_bf16 v[110:113], v[156:159], v[180:183], v[110:113]
	v_mfma_f32_16x16x32_bf16 v[102:105], v[164:167], v[180:183], v[102:105]
	v_mfma_f32_16x16x32_bf16 v[94:97], v[156:159], v[188:191], v[94:97]
	v_mfma_f32_16x16x32_bf16 v[86:89], v[164:167], v[188:191], v[86:89]
	v_mfma_f32_16x16x32_bf16 v[78:81], v[156:159], v[196:199], v[78:81]
	v_mfma_f32_16x16x32_bf16 v[70:73], v[164:167], v[196:199], v[70:73]
	v_mfma_f32_16x16x32_bf16 v[126:129], v[160:163], v[176:179], v[126:129]
	v_mfma_f32_16x16x32_bf16 v[118:121], v[168:171], v[176:179], v[118:121]
	v_mfma_f32_16x16x32_bf16 v[110:113], v[160:163], v[184:187], v[110:113]
	v_mfma_f32_16x16x32_bf16 v[102:105], v[168:171], v[184:187], v[102:105]
	v_mfma_f32_16x16x32_bf16 v[94:97], v[160:163], v[192:195], v[94:97]
	v_mfma_f32_16x16x32_bf16 v[86:89], v[168:171], v[192:195], v[86:89]
	v_mfma_f32_16x16x32_bf16 v[78:81], v[160:163], v[200:203], v[78:81]
	v_mfma_f32_16x16x32_bf16 v[70:73], v[168:171], v[200:203], v[70:73]
	s_barrier
	s_add_u32 s52, s56, 0x80
	s_addc_u32 s53, s57, 0
	ds_read_b128 v[172:175], v138 offset:49152
	ds_read_b128 v[176:179], v138 offset:50176
	ds_read_b128 v[180:183], v138 offset:51200
	ds_read_b128 v[184:187], v138 offset:52224
	ds_read_b128 v[188:191], v138 offset:53248
	ds_read_b128 v[192:195], v138 offset:54272
	ds_read_b128 v[196:199], v138 offset:55296
	ds_read_b128 v[200:203], v138 offset:56320
	s_mov_b32 s12, m0
	s_mov_b32 m0, s76
	s_nop 4
	global_load_lds_dwordx4 v134, s[52:53]
	s_mov_b32 m0, s12
	s_add_u32 s52, s56, 0x20080
	s_addc_u32 s53, s57, 0
	s_mov_b32 s12, m0
	s_mov_b32 m0, s77
	s_nop 4
	global_load_lds_dwordx4 v134, s[52:53]
	s_mov_b32 m0, s12
	s_add_u32 s52, s56, 0x40080
	s_addc_u32 s53, s57, 0
	s_mov_b32 s12, m0
	s_mov_b32 m0, s80
	s_nop 4
	global_load_lds_dwordx4 v134, s[52:53]
	s_mov_b32 m0, s12
	s_add_u32 s52, s56, 0x60080
	s_addc_u32 s53, s57, 0
	s_mov_b32 s12, m0
	s_mov_b32 m0, s81
	s_nop 4
	global_load_lds_dwordx4 v134, s[52:53]
	s_mov_b32 m0, s12
	s_add_u32 s34, s34, 0x20080
	s_mov_b32 s12, m0
	s_mov_b32 m0, s78
	s_nop 4
	global_load_lds_dwordx4 v1, s[54:55]
	s_mov_b32 m0, s12
	s_addc_u32 s35, s35, 0
	s_mov_b32 s12, m0
	s_mov_b32 m0, s79
	s_nop 4
	global_load_lds_dwordx4 v1, s[34:35]
	s_mov_b32 m0, s12
	s_waitcnt vmcnt(8)
	s_waitcnt lgkmcnt(0)
	s_barrier
	s_waitcnt lgkmcnt(7)
	v_mfma_f32_16x16x32_bf16 v[58:61], v[140:143], v[172:175], v[58:61]
	v_mfma_f32_16x16x32_bf16 v[50:53], v[148:151], v[172:175], v[50:53]
	s_waitcnt lgkmcnt(5)
	v_mfma_f32_16x16x32_bf16 v[42:45], v[140:143], v[180:183], v[42:45]
	v_mfma_f32_16x16x32_bf16 v[34:37], v[148:151], v[180:183], v[34:37]
	s_waitcnt lgkmcnt(3)
	v_mfma_f32_16x16x32_bf16 v[26:29], v[140:143], v[188:191], v[26:29]
	v_mfma_f32_16x16x32_bf16 v[18:21], v[148:151], v[188:191], v[18:21]
	s_waitcnt lgkmcnt(1)
	v_mfma_f32_16x16x32_bf16 v[10:13], v[140:143], v[196:199], v[10:13]
	v_mfma_f32_16x16x32_bf16 v[2:5], v[148:151], v[196:199], v[2:5]
	v_mfma_f32_16x16x32_bf16 v[58:61], v[144:147], v[176:179], v[58:61]
	v_mfma_f32_16x16x32_bf16 v[50:53], v[152:155], v[176:179], v[50:53]
	v_mfma_f32_16x16x32_bf16 v[42:45], v[144:147], v[184:187], v[42:45]
	v_mfma_f32_16x16x32_bf16 v[34:37], v[152:155], v[184:187], v[34:37]
	v_mfma_f32_16x16x32_bf16 v[26:29], v[144:147], v[192:195], v[26:29]
	v_mfma_f32_16x16x32_bf16 v[18:21], v[152:155], v[192:195], v[18:21]
	s_waitcnt lgkmcnt(0)
	v_mfma_f32_16x16x32_bf16 v[10:13], v[144:147], v[200:203], v[10:13]
	v_mfma_f32_16x16x32_bf16 v[2:5], v[152:155], v[200:203], v[2:5]
	v_mfma_f32_16x16x32_bf16 v[62:65], v[156:159], v[172:175], v[62:65]
	v_mfma_f32_16x16x32_bf16 v[54:57], v[164:167], v[172:175], v[54:57]
	v_mfma_f32_16x16x32_bf16 v[46:49], v[156:159], v[180:183], v[46:49]
	v_mfma_f32_16x16x32_bf16 v[38:41], v[164:167], v[180:183], v[38:41]
	v_mfma_f32_16x16x32_bf16 v[30:33], v[156:159], v[188:191], v[30:33]
	v_mfma_f32_16x16x32_bf16 v[22:25], v[164:167], v[188:191], v[22:25]
	v_mfma_f32_16x16x32_bf16 v[14:17], v[156:159], v[196:199], v[14:17]
	v_mfma_f32_16x16x32_bf16 v[6:9], v[164:167], v[196:199], v[6:9]
	v_mfma_f32_16x16x32_bf16 v[62:65], v[160:163], v[176:179], v[62:65]
	v_mfma_f32_16x16x32_bf16 v[54:57], v[168:171], v[176:179], v[54:57]
	v_mfma_f32_16x16x32_bf16 v[46:49], v[160:163], v[184:187], v[46:49]
	v_mfma_f32_16x16x32_bf16 v[38:41], v[168:171], v[184:187], v[38:41]
	v_mfma_f32_16x16x32_bf16 v[30:33], v[160:163], v[192:195], v[30:33]
	v_mfma_f32_16x16x32_bf16 v[22:25], v[168:171], v[192:195], v[22:25]
	v_mfma_f32_16x16x32_bf16 v[14:17], v[160:163], v[200:203], v[14:17]
	v_mfma_f32_16x16x32_bf16 v[6:9], v[168:171], v[200:203], v[6:9]
	s_barrier
	s_add_i32 s89, s89, 2
	s_add_u32 s87, s87, 0x100
	s_addc_u32 s88, s88, 0
	s_cmp_gt_u32 s89, 13
	s_mov_b64 s[52:53], s[0:1]
	s_cbranch_scc0 .LBB0_156
	s_and_b64 vcc, exec, s[8:9]
	s_cbranch_vccz .LBB0_159
	s_barrier

.Lwd_1_0:
	s_waitcnt lgkmcnt(0)
	s_barrier
	s_waitcnt lgkmcnt(7)
	v_mfma_f32_16x16x32_bf16 v[122:125], v[142:145], v[174:177], v[122:125]
	v_mfma_f32_16x16x32_bf16 v[114:117], v[150:153], v[174:177], v[114:117]
	s_waitcnt lgkmcnt(5)
	v_mfma_f32_16x16x32_bf16 v[106:109], v[142:145], v[182:185], v[106:109]
	v_mfma_f32_16x16x32_bf16 v[98:101], v[150:153], v[182:185], v[98:101]
	s_waitcnt lgkmcnt(3)
	v_mfma_f32_16x16x32_bf16 v[90:93], v[142:145], v[190:193], v[90:93]
	v_mfma_f32_16x16x32_bf16 v[82:85], v[150:153], v[190:193], v[82:85]
	s_waitcnt lgkmcnt(1)
	v_mfma_f32_16x16x32_bf16 v[74:77], v[142:145], v[198:201], v[74:77]
	v_mfma_f32_16x16x32_bf16 v[66:69], v[150:153], v[198:201], v[66:69]
	v_mfma_f32_16x16x32_bf16 v[122:125], v[146:149], v[178:181], v[122:125]
	v_mfma_f32_16x16x32_bf16 v[114:117], v[154:157], v[178:181], v[114:117]
	v_mfma_f32_16x16x32_bf16 v[106:109], v[146:149], v[186:189], v[106:109]
	v_mfma_f32_16x16x32_bf16 v[98:101], v[154:157], v[186:189], v[98:101]
	v_mfma_f32_16x16x32_bf16 v[90:93], v[146:149], v[194:197], v[90:93]
	v_mfma_f32_16x16x32_bf16 v[82:85], v[154:157], v[194:197], v[82:85]
	s_waitcnt lgkmcnt(0)
	v_mfma_f32_16x16x32_bf16 v[74:77], v[146:149], v[202:205], v[74:77]
	v_mfma_f32_16x16x32_bf16 v[66:69], v[154:157], v[202:205], v[66:69]
	v_mfma_f32_16x16x32_bf16 v[126:129], v[158:161], v[174:177], v[126:129]
	v_mfma_f32_16x16x32_bf16 v[118:121], v[166:169], v[174:177], v[118:121]
	v_mfma_f32_16x16x32_bf16 v[110:113], v[158:161], v[182:185], v[110:113]
	v_mfma_f32_16x16x32_bf16 v[102:105], v[166:169], v[182:185], v[102:105]
	v_mfma_f32_16x16x32_bf16 v[94:97], v[158:161], v[190:193], v[94:97]
	v_mfma_f32_16x16x32_bf16 v[86:89], v[166:169], v[190:193], v[86:89]
	v_mfma_f32_16x16x32_bf16 v[78:81], v[158:161], v[198:201], v[78:81]
	v_mfma_f32_16x16x32_bf16 v[70:73], v[166:169], v[198:201], v[70:73]
	v_mfma_f32_16x16x32_bf16 v[126:129], v[162:165], v[178:181], v[126:129]
	v_mfma_f32_16x16x32_bf16 v[118:121], v[170:173], v[178:181], v[118:121]
	v_mfma_f32_16x16x32_bf16 v[110:113], v[162:165], v[186:189], v[110:113]
	v_mfma_f32_16x16x32_bf16 v[102:105], v[170:173], v[186:189], v[102:105]
	v_mfma_f32_16x16x32_bf16 v[94:97], v[162:165], v[194:197], v[94:97]
	v_mfma_f32_16x16x32_bf16 v[86:89], v[170:173], v[194:197], v[86:89]
	v_mfma_f32_16x16x32_bf16 v[78:81], v[162:165], v[202:205], v[78:81]
	v_mfma_f32_16x16x32_bf16 v[70:73], v[170:173], v[202:205], v[70:73]
	s_barrier
	s_add_u32 s44, s52, 0x20000
	ds_read_b128 v[174:177], v140 offset:16384
	ds_read_b128 v[178:181], v140 offset:17408
	ds_read_b128 v[182:185], v140 offset:18432
	ds_read_b128 v[186:189], v140 offset:19456
	ds_read_b128 v[190:193], v140 offset:20480
	ds_read_b128 v[194:197], v140 offset:21504
	ds_read_b128 v[198:201], v140 offset:22528
	ds_read_b128 v[202:205], v140 offset:23552
	s_mov_b32 s2, m0
	s_mov_b32 m0, s56
	s_nop 4
	global_load_lds_dwordx4 v136, s[52:53]
	s_mov_b32 m0, s2
	s_addc_u32 s45, s53, 0
	s_mov_b32 s2, m0
	s_mov_b32 m0, s57
	s_nop 4
	global_load_lds_dwordx4 v136, s[44:45]
	s_mov_b32 m0, s2
	s_add_u32 s44, s52, 0x40000
	s_addc_u32 s45, s53, 0
	s_mov_b32 s2, m0
	s_mov_b32 m0, s58
	s_nop 4
	global_load_lds_dwordx4 v136, s[44:45]
	s_mov_b32 m0, s2
	s_add_u32 s44, s52, 0x60000
	s_addc_u32 s45, s53, 0
	s_mov_b32 s2, m0
	s_mov_b32 m0, s59
	s_nop 4
	global_load_lds_dwordx4 v136, s[44:45]
	s_mov_b32 m0, s2
	s_add_u32 s44, s34, 0x20000
	s_mov_b32 s2, m0
	s_mov_b32 m0, s43
	s_nop 4
	global_load_lds_dwordx4 v1, s[34:35]
	s_mov_b32 m0, s2
	s_addc_u32 s45, s35, 0
	s_mov_b32 s2, m0
	s_mov_b32 m0, s60
	s_nop 4
	global_load_lds_dwordx4 v1, s[44:45]
	s_mov_b32 m0, s2
	s_cmp_eq_u32 s81, -2
	s_cselect_b32 s99, s98, 0
	s_cmp_eq_u32 s99, 0
	s_cbranch_scc1 .Lw8_1_1
	s_waitcnt vmcnt(16)
	s_branch .Lwd_1_1

.Lwd_1_1:
	s_waitcnt lgkmcnt(0)
	s_barrier
	s_waitcnt lgkmcnt(7)
	v_mfma_f32_16x16x32_bf16 v[58:61], v[142:145], v[174:177], v[58:61]
	v_mfma_f32_16x16x32_bf16 v[50:53], v[150:153], v[174:177], v[50:53]
	s_waitcnt lgkmcnt(5)
	v_mfma_f32_16x16x32_bf16 v[42:45], v[142:145], v[182:185], v[42:45]
	v_mfma_f32_16x16x32_bf16 v[34:37], v[150:153], v[182:185], v[34:37]
	s_waitcnt lgkmcnt(3)
	v_mfma_f32_16x16x32_bf16 v[26:29], v[142:145], v[190:193], v[26:29]
	v_mfma_f32_16x16x32_bf16 v[18:21], v[150:153], v[190:193], v[18:21]
	s_waitcnt lgkmcnt(1)
	v_mfma_f32_16x16x32_bf16 v[10:13], v[142:145], v[198:201], v[10:13]
	v_mfma_f32_16x16x32_bf16 v[6:9], v[150:153], v[198:201], v[6:9]
	v_mfma_f32_16x16x32_bf16 v[58:61], v[146:149], v[178:181], v[58:61]
	v_mfma_f32_16x16x32_bf16 v[50:53], v[154:157], v[178:181], v[50:53]
	v_mfma_f32_16x16x32_bf16 v[42:45], v[146:149], v[186:189], v[42:45]
	v_mfma_f32_16x16x32_bf16 v[34:37], v[154:157], v[186:189], v[34:37]
	v_mfma_f32_16x16x32_bf16 v[26:29], v[146:149], v[194:197], v[26:29]
	v_mfma_f32_16x16x32_bf16 v[18:21], v[154:157], v[194:197], v[18:21]
	s_waitcnt lgkmcnt(0)
	v_mfma_f32_16x16x32_bf16 v[10:13], v[146:149], v[202:205], v[10:13]
	v_mfma_f32_16x16x32_bf16 v[6:9], v[154:157], v[202:205], v[6:9]
	v_mfma_f32_16x16x32_bf16 v[62:65], v[158:161], v[174:177], v[62:65]
	v_mfma_f32_16x16x32_bf16 v[54:57], v[166:169], v[174:177], v[54:57]
	v_mfma_f32_16x16x32_bf16 v[46:49], v[158:161], v[182:185], v[46:49]
	v_mfma_f32_16x16x32_bf16 v[38:41], v[166:169], v[182:185], v[38:41]
	v_mfma_f32_16x16x32_bf16 v[30:33], v[158:161], v[190:193], v[30:33]
	v_mfma_f32_16x16x32_bf16 v[22:25], v[166:169], v[190:193], v[22:25]
	v_mfma_f32_16x16x32_bf16 v[14:17], v[158:161], v[198:201], v[14:17]
	v_mfma_f32_16x16x32_bf16 v[2:5], v[166:169], v[198:201], v[2:5]
	v_mfma_f32_16x16x32_bf16 v[62:65], v[162:165], v[178:181], v[62:65]
	v_mfma_f32_16x16x32_bf16 v[54:57], v[170:173], v[178:181], v[54:57]
	v_mfma_f32_16x16x32_bf16 v[46:49], v[162:165], v[186:189], v[46:49]
	v_mfma_f32_16x16x32_bf16 v[38:41], v[170:173], v[186:189], v[38:41]
	v_mfma_f32_16x16x32_bf16 v[30:33], v[162:165], v[194:197], v[30:33]
	v_mfma_f32_16x16x32_bf16 v[22:25], v[170:173], v[194:197], v[22:25]
	v_mfma_f32_16x16x32_bf16 v[14:17], v[162:165], v[202:205], v[14:17]
	v_mfma_f32_16x16x32_bf16 v[2:5], v[170:173], v[202:205], v[2:5]
	s_barrier
	v_add_u32_e32 v134, 0x18000, v139
	ds_read_b128 v[142:145], v134
	ds_read_b128 v[146:149], v134 offset:1024
	ds_read_b128 v[150:153], v134 offset:2048
	ds_read_b128 v[154:157], v134 offset:3072
	v_add_u32_e32 v134, 0x1c000, v139
	ds_read_b128 v[158:161], v134
	ds_read_b128 v[162:165], v134 offset:1024
	ds_read_b128 v[166:169], v134 offset:2048
	ds_read_b128 v[170:173], v134 offset:3072
	ds_read_b128 v[174:177], v140 offset:32768
	ds_read_b128 v[178:181], v140 offset:33792
	ds_read_b128 v[182:185], v140 offset:34816
	ds_read_b128 v[186:189], v140 offset:35840
	ds_read_b128 v[190:193], v140 offset:36864
	ds_read_b128 v[194:197], v140 offset:37888
	ds_read_b128 v[198:201], v140 offset:38912
	ds_read_b128 v[202:205], v140 offset:39936
	s_add_u32 s44, s34, 0x40000
	s_addc_u32 s45, s35, 0
	s_mov_b32 s2, m0
	s_mov_b32 m0, s61
	s_nop 4
	global_load_lds_dwordx4 v1, s[44:45]
	s_mov_b32 m0, s2
	s_add_u32 s44, s34, 0x60000
	s_addc_u32 s45, s35, 0
	s_mov_b32 s2, m0
	s_mov_b32 m0, s62
	s_nop 4
	global_load_lds_dwordx4 v1, s[44:45]
	s_mov_b32 m0, s2
	s_waitcnt vmcnt(8)
	s_waitcnt lgkmcnt(0)
	s_barrier
	s_waitcnt lgkmcnt(7)
	v_mfma_f32_16x16x32_bf16 v[122:125], v[142:145], v[174:177], v[122:125]
	v_mfma_f32_16x16x32_bf16 v[114:117], v[150:153], v[174:177], v[114:117]
	s_waitcnt lgkmcnt(5)
	v_mfma_f32_16x16x32_bf16 v[106:109], v[142:145], v[182:185], v[106:109]
	v_mfma_f32_16x16x32_bf16 v[98:101], v[150:153], v[182:185], v[98:101]
	s_waitcnt lgkmcnt(3)
	v_mfma_f32_16x16x32_bf16 v[90:93], v[142:145], v[190:193], v[90:93]
	v_mfma_f32_16x16x32_bf16 v[82:85], v[150:153], v[190:193], v[82:85]
	s_waitcnt lgkmcnt(1)
	v_mfma_f32_16x16x32_bf16 v[74:77], v[142:145], v[198:201], v[74:77]
	v_mfma_f32_16x16x32_bf16 v[66:69], v[150:153], v[198:201], v[66:69]
	v_mfma_f32_16x16x32_bf16 v[122:125], v[146:149], v[178:181], v[122:125]
	v_mfma_f32_16x16x32_bf16 v[114:117], v[154:157], v[178:181], v[114:117]
	v_mfma_f32_16x16x32_bf16 v[106:109], v[146:149], v[186:189], v[106:109]
	v_mfma_f32_16x16x32_bf16 v[98:101], v[154:157], v[186:189], v[98:101]
	v_mfma_f32_16x16x32_bf16 v[90:93], v[146:149], v[194:197], v[90:93]
	v_mfma_f32_16x16x32_bf16 v[82:85], v[154:157], v[194:197], v[82:85]
	s_waitcnt lgkmcnt(0)
	v_mfma_f32_16x16x32_bf16 v[74:77], v[146:149], v[202:205], v[74:77]
	v_mfma_f32_16x16x32_bf16 v[66:69], v[154:157], v[202:205], v[66:69]
	v_mfma_f32_16x16x32_bf16 v[126:129], v[158:161], v[174:177], v[126:129]
	v_mfma_f32_16x16x32_bf16 v[118:121], v[166:169], v[174:177], v[118:121]
	v_mfma_f32_16x16x32_bf16 v[110:113], v[158:161], v[182:185], v[110:113]
	v_mfma_f32_16x16x32_bf16 v[102:105], v[166:169], v[182:185], v[102:105]
	v_mfma_f32_16x16x32_bf16 v[94:97], v[158:161], v[190:193], v[94:97]
	v_mfma_f32_16x16x32_bf16 v[86:89], v[166:169], v[190:193], v[86:89]
	v_mfma_f32_16x16x32_bf16 v[78:81], v[158:161], v[198:201], v[78:81]
	v_mfma_f32_16x16x32_bf16 v[70:73], v[166:169], v[198:201], v[70:73]
	v_mfma_f32_16x16x32_bf16 v[126:129], v[162:165], v[178:181], v[126:129]
	v_mfma_f32_16x16x32_bf16 v[118:121], v[170:173], v[178:181], v[118:121]
	v_mfma_f32_16x16x32_bf16 v[110:113], v[162:165], v[186:189], v[110:113]
	v_mfma_f32_16x16x32_bf16 v[102:105], v[170:173], v[186:189], v[102:105]
	v_mfma_f32_16x16x32_bf16 v[94:97], v[162:165], v[194:197], v[94:97]
	v_mfma_f32_16x16x32_bf16 v[86:89], v[170:173], v[194:197], v[86:89]
	v_mfma_f32_16x16x32_bf16 v[78:81], v[162:165], v[202:205], v[78:81]
	v_mfma_f32_16x16x32_bf16 v[70:73], v[170:173], v[202:205], v[70:73]
	s_barrier
	s_add_u32 s44, s52, 0x80
	s_addc_u32 s45, s53, 0
	ds_read_b128 v[174:177], v140 offset:49152
	ds_read_b128 v[178:181], v140 offset:50176
	ds_read_b128 v[182:185], v140 offset:51200
	ds_read_b128 v[186:189], v140 offset:52224
	ds_read_b128 v[190:193], v140 offset:53248
	ds_read_b128 v[194:197], v140 offset:54272
	ds_read_b128 v[198:201], v140 offset:55296
	ds_read_b128 v[202:205], v140 offset:56320
	s_mov_b32 s2, m0
	s_mov_b32 m0, s63
	s_nop 4
	global_load_lds_dwordx4 v136, s[44:45]
	s_mov_b32 m0, s2
	s_add_u32 s44, s52, 0x20080
	s_addc_u32 s45, s53, 0
	s_mov_b32 s2, m0
	s_mov_b32 m0, s64
	s_nop 4
	global_load_lds_dwordx4 v136, s[44:45]
	s_mov_b32 m0, s2
	s_add_u32 s44, s52, 0x40080
	s_addc_u32 s45, s53, 0
	s_mov_b32 s2, m0
	s_mov_b32 m0, s67
	s_nop 4
	global_load_lds_dwordx4 v136, s[44:45]
	s_mov_b32 m0, s2
	s_add_u32 s44, s52, 0x60080
	s_addc_u32 s45, s53, 0
	s_mov_b32 s2, m0
	s_mov_b32 m0, s73
	s_nop 4
	global_load_lds_dwordx4 v136, s[44:45]
	s_mov_b32 m0, s2
	s_add_u32 s34, s34, 0x20080
	s_mov_b32 s2, m0
	s_mov_b32 m0, s65
	s_nop 4
	global_load_lds_dwordx4 v1, s[50:51]
	s_mov_b32 m0, s2
	s_addc_u32 s35, s35, 0
	s_mov_b32 s2, m0
	s_mov_b32 m0, s66
	s_nop 4
	global_load_lds_dwordx4 v1, s[34:35]
	s_mov_b32 m0, s2
	s_waitcnt vmcnt(8)
	s_waitcnt lgkmcnt(0)
	s_barrier
	s_waitcnt lgkmcnt(7)
	v_mfma_f32_16x16x32_bf16 v[58:61], v[142:145], v[174:177], v[58:61]
	v_mfma_f32_16x16x32_bf16 v[50:53], v[150:153], v[174:177], v[50:53]
	s_waitcnt lgkmcnt(5)
	v_mfma_f32_16x16x32_bf16 v[42:45], v[142:145], v[182:185], v[42:45]
	v_mfma_f32_16x16x32_bf16 v[34:37], v[150:153], v[182:185], v[34:37]
	s_waitcnt lgkmcnt(3)
	v_mfma_f32_16x16x32_bf16 v[26:29], v[142:145], v[190:193], v[26:29]
	v_mfma_f32_16x16x32_bf16 v[18:21], v[150:153], v[190:193], v[18:21]
	s_waitcnt lgkmcnt(1)
	v_mfma_f32_16x16x32_bf16 v[10:13], v[142:145], v[198:201], v[10:13]
	v_mfma_f32_16x16x32_bf16 v[6:9], v[150:153], v[198:201], v[6:9]
	v_mfma_f32_16x16x32_bf16 v[58:61], v[146:149], v[178:181], v[58:61]
	v_mfma_f32_16x16x32_bf16 v[50:53], v[154:157], v[178:181], v[50:53]
	v_mfma_f32_16x16x32_bf16 v[42:45], v[146:149], v[186:189], v[42:45]
	v_mfma_f32_16x16x32_bf16 v[34:37], v[154:157], v[186:189], v[34:37]
	v_mfma_f32_16x16x32_bf16 v[26:29], v[146:149], v[194:197], v[26:29]
	v_mfma_f32_16x16x32_bf16 v[18:21], v[154:157], v[194:197], v[18:21]
	s_waitcnt lgkmcnt(0)
	v_mfma_f32_16x16x32_bf16 v[10:13], v[146:149], v[202:205], v[10:13]
	v_mfma_f32_16x16x32_bf16 v[6:9], v[154:157], v[202:205], v[6:9]
	v_mfma_f32_16x16x32_bf16 v[62:65], v[158:161], v[174:177], v[62:65]
	v_mfma_f32_16x16x32_bf16 v[54:57], v[166:169], v[174:177], v[54:57]
	v_mfma_f32_16x16x32_bf16 v[46:49], v[158:161], v[182:185], v[46:49]
	v_mfma_f32_16x16x32_bf16 v[38:41], v[166:169], v[182:185], v[38:41]
	v_mfma_f32_16x16x32_bf16 v[30:33], v[158:161], v[190:193], v[30:33]
	v_mfma_f32_16x16x32_bf16 v[22:25], v[166:169], v[190:193], v[22:25]
	v_mfma_f32_16x16x32_bf16 v[14:17], v[158:161], v[198:201], v[14:17]
	v_mfma_f32_16x16x32_bf16 v[2:5], v[166:169], v[198:201], v[2:5]
	v_mfma_f32_16x16x32_bf16 v[62:65], v[162:165], v[178:181], v[62:65]
	v_mfma_f32_16x16x32_bf16 v[54:57], v[170:173], v[178:181], v[54:57]
	v_mfma_f32_16x16x32_bf16 v[46:49], v[162:165], v[186:189], v[46:49]
	v_mfma_f32_16x16x32_bf16 v[38:41], v[170:173], v[186:189], v[38:41]
	v_mfma_f32_16x16x32_bf16 v[30:33], v[162:165], v[194:197], v[30:33]
	v_mfma_f32_16x16x32_bf16 v[22:25], v[170:173], v[194:197], v[22:25]
	v_mfma_f32_16x16x32_bf16 v[14:17], v[162:165], v[202:205], v[14:17]
	v_mfma_f32_16x16x32_bf16 v[2:5], v[170:173], v[202:205], v[2:5]
	s_barrier
	s_add_i32 s81, s81, 2
	s_add_u32 s79, s79, 0x100
	s_addc_u32 s80, s80, 0
	s_cmp_gt_u32 s81, 13
	s_mov_b64 s[44:45], s[0:1]
	s_cbranch_scc0 .LBB0_557
	s_and_b64 vcc, exec, s[10:11]
	s_cbranch_vccz .LBB0_560
	s_barrier

.Lwd_2_0:
	s_waitcnt lgkmcnt(0)
	s_barrier
	s_waitcnt lgkmcnt(7)
	v_mfma_f32_16x16x32_bf16 v[122:125], v[142:145], v[174:177], v[122:125]
	v_mfma_f32_16x16x32_bf16 v[114:117], v[150:153], v[174:177], v[114:117]
	s_waitcnt lgkmcnt(5)
	v_mfma_f32_16x16x32_bf16 v[106:109], v[142:145], v[182:185], v[106:109]
	v_mfma_f32_16x16x32_bf16 v[98:101], v[150:153], v[182:185], v[98:101]
	s_waitcnt lgkmcnt(3)
	v_mfma_f32_16x16x32_bf16 v[90:93], v[142:145], v[190:193], v[90:93]
	v_mfma_f32_16x16x32_bf16 v[82:85], v[150:153], v[190:193], v[82:85]
	s_waitcnt lgkmcnt(1)
	v_mfma_f32_16x16x32_bf16 v[74:77], v[142:145], v[198:201], v[74:77]
	v_mfma_f32_16x16x32_bf16 v[66:69], v[150:153], v[198:201], v[66:69]
	v_mfma_f32_16x16x32_bf16 v[122:125], v[146:149], v[178:181], v[122:125]
	v_mfma_f32_16x16x32_bf16 v[114:117], v[154:157], v[178:181], v[114:117]
	v_mfma_f32_16x16x32_bf16 v[106:109], v[146:149], v[186:189], v[106:109]
	v_mfma_f32_16x16x32_bf16 v[98:101], v[154:157], v[186:189], v[98:101]
	v_mfma_f32_16x16x32_bf16 v[90:93], v[146:149], v[194:197], v[90:93]
	v_mfma_f32_16x16x32_bf16 v[82:85], v[154:157], v[194:197], v[82:85]
	s_waitcnt lgkmcnt(0)
	v_mfma_f32_16x16x32_bf16 v[74:77], v[146:149], v[202:205], v[74:77]
	v_mfma_f32_16x16x32_bf16 v[66:69], v[154:157], v[202:205], v[66:69]
	v_mfma_f32_16x16x32_bf16 v[126:129], v[158:161], v[174:177], v[126:129]
	v_mfma_f32_16x16x32_bf16 v[118:121], v[166:169], v[174:177], v[118:121]
	v_mfma_f32_16x16x32_bf16 v[110:113], v[158:161], v[182:185], v[110:113]
	v_mfma_f32_16x16x32_bf16 v[102:105], v[166:169], v[182:185], v[102:105]
	v_mfma_f32_16x16x32_bf16 v[94:97], v[158:161], v[190:193], v[94:97]
	v_mfma_f32_16x16x32_bf16 v[86:89], v[166:169], v[190:193], v[86:89]
	v_mfma_f32_16x16x32_bf16 v[78:81], v[158:161], v[198:201], v[78:81]
	v_mfma_f32_16x16x32_bf16 v[70:73], v[166:169], v[198:201], v[70:73]
	v_mfma_f32_16x16x32_bf16 v[126:129], v[162:165], v[178:181], v[126:129]
	v_mfma_f32_16x16x32_bf16 v[118:121], v[170:173], v[178:181], v[118:121]
	v_mfma_f32_16x16x32_bf16 v[110:113], v[162:165], v[186:189], v[110:113]
	v_mfma_f32_16x16x32_bf16 v[102:105], v[170:173], v[186:189], v[102:105]
	v_mfma_f32_16x16x32_bf16 v[94:97], v[162:165], v[194:197], v[94:97]
	v_mfma_f32_16x16x32_bf16 v[86:89], v[170:173], v[194:197], v[86:89]
	v_mfma_f32_16x16x32_bf16 v[78:81], v[162:165], v[202:205], v[78:81]
	v_mfma_f32_16x16x32_bf16 v[70:73], v[170:173], v[202:205], v[70:73]
	s_barrier
	ds_read_b128 v[174:177], v140 offset:16384
	ds_read_b128 v[178:181], v140 offset:17408
	ds_read_b128 v[182:185], v140 offset:18432
	ds_read_b128 v[186:189], v140 offset:19456
	ds_read_b128 v[190:193], v140 offset:20480
	ds_read_b128 v[194:197], v140 offset:21504
	ds_read_b128 v[198:201], v140 offset:22528
	ds_read_b128 v[202:205], v140 offset:23552
	s_mov_b32 s2, m0
	s_mov_b32 m0, s54
	s_nop 4
	global_load_lds_dwordx4 v136, s[50:51]
	s_mov_b32 m0, s2
	s_add_u32 s2, s50, 0x20000
	s_addc_u32 s3, s51, 0
	s_mov_b32 s12, m0
	s_mov_b32 m0, s55
	s_nop 4
	global_load_lds_dwordx4 v136, s[2:3]
	s_mov_b32 m0, s12
	s_add_u32 s2, s50, 0x40000
	s_addc_u32 s3, s51, 0
	s_mov_b32 s12, m0
	s_mov_b32 m0, s56
	s_nop 4
	global_load_lds_dwordx4 v136, s[2:3]
	s_mov_b32 m0, s12
	s_add_u32 s2, s50, 0x60000
	s_addc_u32 s3, s51, 0
	s_mov_b32 s12, m0
	s_mov_b32 m0, s57
	s_nop 4
	global_load_lds_dwordx4 v136, s[2:3]
	s_mov_b32 m0, s12
	s_mov_b32 s2, m0
	s_mov_b32 m0, s39
	s_nop 4
	global_load_lds_dwordx4 v1, s[34:35]
	s_mov_b32 m0, s2
	s_add_u32 s2, s34, 0x20000
	s_addc_u32 s3, s35, 0
	s_mov_b32 s12, m0
	s_mov_b32 m0, s58
	s_nop 4
	global_load_lds_dwordx4 v1, s[2:3]
	s_mov_b32 m0, s12
	s_cmp_eq_u32 s88, -2
	s_cselect_b32 s99, s98, 0
	s_cmp_eq_u32 s99, 0
	s_cbranch_scc1 .Lw8_2_1
	s_waitcnt vmcnt(16)
	s_branch .Lwd_2_1

.Lwd_2_1:
	s_waitcnt lgkmcnt(0)
	s_barrier
	s_waitcnt lgkmcnt(7)
	v_mfma_f32_16x16x32_bf16 v[58:61], v[142:145], v[174:177], v[58:61]
	v_mfma_f32_16x16x32_bf16 v[50:53], v[150:153], v[174:177], v[50:53]
	s_waitcnt lgkmcnt(5)
	v_mfma_f32_16x16x32_bf16 v[42:45], v[142:145], v[182:185], v[42:45]
	v_mfma_f32_16x16x32_bf16 v[34:37], v[150:153], v[182:185], v[34:37]
	s_waitcnt lgkmcnt(3)
	v_mfma_f32_16x16x32_bf16 v[26:29], v[142:145], v[190:193], v[26:29]
	v_mfma_f32_16x16x32_bf16 v[18:21], v[150:153], v[190:193], v[18:21]
	s_waitcnt lgkmcnt(1)
	v_mfma_f32_16x16x32_bf16 v[10:13], v[142:145], v[198:201], v[10:13]
	v_mfma_f32_16x16x32_bf16 v[6:9], v[150:153], v[198:201], v[6:9]
	v_mfma_f32_16x16x32_bf16 v[58:61], v[146:149], v[178:181], v[58:61]
	v_mfma_f32_16x16x32_bf16 v[50:53], v[154:157], v[178:181], v[50:53]
	v_mfma_f32_16x16x32_bf16 v[42:45], v[146:149], v[186:189], v[42:45]
	v_mfma_f32_16x16x32_bf16 v[34:37], v[154:157], v[186:189], v[34:37]
	v_mfma_f32_16x16x32_bf16 v[26:29], v[146:149], v[194:197], v[26:29]
	v_mfma_f32_16x16x32_bf16 v[18:21], v[154:157], v[194:197], v[18:21]
	s_waitcnt lgkmcnt(0)
	v_mfma_f32_16x16x32_bf16 v[10:13], v[146:149], v[202:205], v[10:13]
	v_mfma_f32_16x16x32_bf16 v[6:9], v[154:157], v[202:205], v[6:9]
	v_mfma_f32_16x16x32_bf16 v[62:65], v[158:161], v[174:177], v[62:65]
	v_mfma_f32_16x16x32_bf16 v[54:57], v[166:169], v[174:177], v[54:57]
	v_mfma_f32_16x16x32_bf16 v[46:49], v[158:161], v[182:185], v[46:49]
	v_mfma_f32_16x16x32_bf16 v[38:41], v[166:169], v[182:185], v[38:41]
	v_mfma_f32_16x16x32_bf16 v[30:33], v[158:161], v[190:193], v[30:33]
	v_mfma_f32_16x16x32_bf16 v[22:25], v[166:169], v[190:193], v[22:25]
	v_mfma_f32_16x16x32_bf16 v[14:17], v[158:161], v[198:201], v[14:17]
	v_mfma_f32_16x16x32_bf16 v[2:5], v[166:169], v[198:201], v[2:5]
	v_mfma_f32_16x16x32_bf16 v[62:65], v[162:165], v[178:181], v[62:65]
	v_mfma_f32_16x16x32_bf16 v[54:57], v[170:173], v[178:181], v[54:57]
	v_mfma_f32_16x16x32_bf16 v[46:49], v[162:165], v[186:189], v[46:49]
	v_mfma_f32_16x16x32_bf16 v[38:41], v[170:173], v[186:189], v[38:41]
	v_mfma_f32_16x16x32_bf16 v[30:33], v[162:165], v[194:197], v[30:33]
	v_mfma_f32_16x16x32_bf16 v[22:25], v[170:173], v[194:197], v[22:25]
	v_mfma_f32_16x16x32_bf16 v[14:17], v[162:165], v[202:205], v[14:17]
	v_mfma_f32_16x16x32_bf16 v[2:5], v[170:173], v[202:205], v[2:5]
	s_barrier
	v_add_u32_e32 v134, 0x18000, v139
	ds_read_b128 v[142:145], v134
	ds_read_b128 v[146:149], v134 offset:1024
	ds_read_b128 v[150:153], v134 offset:2048
	ds_read_b128 v[154:157], v134 offset:3072
	v_add_u32_e32 v134, 0x1c000, v139
	ds_read_b128 v[158:161], v134
	ds_read_b128 v[162:165], v134 offset:1024
	ds_read_b128 v[166:169], v134 offset:2048
	ds_read_b128 v[170:173], v134 offset:3072
	ds_read_b128 v[174:177], v140 offset:32768
	ds_read_b128 v[178:181], v140 offset:33792
	ds_read_b128 v[182:185], v140 offset:34816
	ds_read_b128 v[186:189], v140 offset:35840
	ds_read_b128 v[190:193], v140 offset:36864
	ds_read_b128 v[194:197], v140 offset:37888
	ds_read_b128 v[198:201], v140 offset:38912
	ds_read_b128 v[202:205], v140 offset:39936
	s_add_u32 s2, s34, 0x40000
	s_addc_u32 s3, s35, 0
	s_mov_b32 s12, m0
	s_mov_b32 m0, s59
	s_nop 4
	global_load_lds_dwordx4 v1, s[2:3]
	s_mov_b32 m0, s12
	s_add_u32 s2, s34, 0x60000
	s_addc_u32 s3, s35, 0
	s_mov_b32 s12, m0
	s_mov_b32 m0, s60
	s_nop 4
	global_load_lds_dwordx4 v1, s[2:3]
	s_mov_b32 m0, s12
	s_waitcnt vmcnt(8)
	s_waitcnt lgkmcnt(0)
	s_barrier
	s_waitcnt lgkmcnt(7)
	v_mfma_f32_16x16x32_bf16 v[122:125], v[142:145], v[174:177], v[122:125]
	v_mfma_f32_16x16x32_bf16 v[114:117], v[150:153], v[174:177], v[114:117]
	s_waitcnt lgkmcnt(5)
	v_mfma_f32_16x16x32_bf16 v[106:109], v[142:145], v[182:185], v[106:109]
	v_mfma_f32_16x16x32_bf16 v[98:101], v[150:153], v[182:185], v[98:101]
	s_waitcnt lgkmcnt(3)
	v_mfma_f32_16x16x32_bf16 v[90:93], v[142:145], v[190:193], v[90:93]
	v_mfma_f32_16x16x32_bf16 v[82:85], v[150:153], v[190:193], v[82:85]
	s_waitcnt lgkmcnt(1)
	v_mfma_f32_16x16x32_bf16 v[74:77], v[142:145], v[198:201], v[74:77]
	v_mfma_f32_16x16x32_bf16 v[66:69], v[150:153], v[198:201], v[66:69]
	v_mfma_f32_16x16x32_bf16 v[122:125], v[146:149], v[178:181], v[122:125]
	v_mfma_f32_16x16x32_bf16 v[114:117], v[154:157], v[178:181], v[114:117]
	v_mfma_f32_16x16x32_bf16 v[106:109], v[146:149], v[186:189], v[106:109]
	v_mfma_f32_16x16x32_bf16 v[98:101], v[154:157], v[186:189], v[98:101]
	v_mfma_f32_16x16x32_bf16 v[90:93], v[146:149], v[194:197], v[90:93]
	v_mfma_f32_16x16x32_bf16 v[82:85], v[154:157], v[194:197], v[82:85]
	s_waitcnt lgkmcnt(0)
	v_mfma_f32_16x16x32_bf16 v[74:77], v[146:149], v[202:205], v[74:77]
	v_mfma_f32_16x16x32_bf16 v[66:69], v[154:157], v[202:205], v[66:69]
	v_mfma_f32_16x16x32_bf16 v[126:129], v[158:161], v[174:177], v[126:129]
	v_mfma_f32_16x16x32_bf16 v[118:121], v[166:169], v[174:177], v[118:121]
	v_mfma_f32_16x16x32_bf16 v[110:113], v[158:161], v[182:185], v[110:113]
	v_mfma_f32_16x16x32_bf16 v[102:105], v[166:169], v[182:185], v[102:105]
	v_mfma_f32_16x16x32_bf16 v[94:97], v[158:161], v[190:193], v[94:97]
	v_mfma_f32_16x16x32_bf16 v[86:89], v[166:169], v[190:193], v[86:89]
	v_mfma_f32_16x16x32_bf16 v[78:81], v[158:161], v[198:201], v[78:81]
	v_mfma_f32_16x16x32_bf16 v[70:73], v[166:169], v[198:201], v[70:73]
	v_mfma_f32_16x16x32_bf16 v[126:129], v[162:165], v[178:181], v[126:129]
	v_mfma_f32_16x16x32_bf16 v[118:121], v[170:173], v[178:181], v[118:121]
	v_mfma_f32_16x16x32_bf16 v[110:113], v[162:165], v[186:189], v[110:113]
	v_mfma_f32_16x16x32_bf16 v[102:105], v[170:173], v[186:189], v[102:105]
	v_mfma_f32_16x16x32_bf16 v[94:97], v[162:165], v[194:197], v[94:97]
	v_mfma_f32_16x16x32_bf16 v[86:89], v[170:173], v[194:197], v[86:89]
	v_mfma_f32_16x16x32_bf16 v[78:81], v[162:165], v[202:205], v[78:81]
	v_mfma_f32_16x16x32_bf16 v[70:73], v[170:173], v[202:205], v[70:73]
	s_barrier
	s_add_u32 s2, s50, 0x80
	s_addc_u32 s3, s51, 0
	ds_read_b128 v[174:177], v140 offset:49152
	ds_read_b128 v[178:181], v140 offset:50176
	ds_read_b128 v[182:185], v140 offset:51200
	ds_read_b128 v[186:189], v140 offset:52224
	ds_read_b128 v[190:193], v140 offset:53248
	ds_read_b128 v[194:197], v140 offset:54272
	ds_read_b128 v[198:201], v140 offset:55296
	ds_read_b128 v[202:205], v140 offset:56320
	s_mov_b32 s12, m0
	s_mov_b32 m0, s61
	s_nop 4
	global_load_lds_dwordx4 v136, s[2:3]
	s_mov_b32 m0, s12
	s_add_u32 s2, s50, 0x20080
	s_addc_u32 s3, s51, 0
	s_mov_b32 s12, m0
	s_mov_b32 m0, s62
	s_nop 4
	global_load_lds_dwordx4 v136, s[2:3]
	s_mov_b32 m0, s12
	s_add_u32 s2, s50, 0x40080
	s_addc_u32 s3, s51, 0
	s_mov_b32 s12, m0
	s_mov_b32 m0, s65
	s_nop 4
	global_load_lds_dwordx4 v136, s[2:3]
	s_mov_b32 m0, s12
	s_add_u32 s2, s50, 0x60080
	s_addc_u32 s3, s51, 0
	s_mov_b32 s12, m0
	s_mov_b32 m0, s66
	s_nop 4
	global_load_lds_dwordx4 v136, s[2:3]
	s_mov_b32 m0, s12
	s_mov_b32 s2, m0
	s_mov_b32 m0, s63
	s_nop 4
	global_load_lds_dwordx4 v1, s[44:45]
	s_mov_b32 m0, s2
	s_add_u32 s2, s34, 0x20080
	s_addc_u32 s3, s35, 0
	s_mov_b32 s12, m0
	s_mov_b32 m0, s64
	s_nop 4
	global_load_lds_dwordx4 v1, s[2:3]
	s_mov_b32 m0, s12
	s_waitcnt vmcnt(8)
	s_waitcnt lgkmcnt(0)
	s_barrier
	s_waitcnt lgkmcnt(7)
	v_mfma_f32_16x16x32_bf16 v[58:61], v[142:145], v[174:177], v[58:61]
	v_mfma_f32_16x16x32_bf16 v[50:53], v[150:153], v[174:177], v[50:53]
	s_waitcnt lgkmcnt(5)
	v_mfma_f32_16x16x32_bf16 v[42:45], v[142:145], v[182:185], v[42:45]
	v_mfma_f32_16x16x32_bf16 v[34:37], v[150:153], v[182:185], v[34:37]
	s_waitcnt lgkmcnt(3)
	v_mfma_f32_16x16x32_bf16 v[26:29], v[142:145], v[190:193], v[26:29]
	v_mfma_f32_16x16x32_bf16 v[18:21], v[150:153], v[190:193], v[18:21]
	s_waitcnt lgkmcnt(1)
	v_mfma_f32_16x16x32_bf16 v[10:13], v[142:145], v[198:201], v[10:13]
	v_mfma_f32_16x16x32_bf16 v[6:9], v[150:153], v[198:201], v[6:9]
	v_mfma_f32_16x16x32_bf16 v[58:61], v[146:149], v[178:181], v[58:61]
	v_mfma_f32_16x16x32_bf16 v[50:53], v[154:157], v[178:181], v[50:53]
	v_mfma_f32_16x16x32_bf16 v[42:45], v[146:149], v[186:189], v[42:45]
	v_mfma_f32_16x16x32_bf16 v[34:37], v[154:157], v[186:189], v[34:37]
	v_mfma_f32_16x16x32_bf16 v[26:29], v[146:149], v[194:197], v[26:29]
	v_mfma_f32_16x16x32_bf16 v[18:21], v[154:157], v[194:197], v[18:21]
	s_waitcnt lgkmcnt(0)
	v_mfma_f32_16x16x32_bf16 v[10:13], v[146:149], v[202:205], v[10:13]
	v_mfma_f32_16x16x32_bf16 v[6:9], v[154:157], v[202:205], v[6:9]
	v_mfma_f32_16x16x32_bf16 v[62:65], v[158:161], v[174:177], v[62:65]
	v_mfma_f32_16x16x32_bf16 v[54:57], v[166:169], v[174:177], v[54:57]
	v_mfma_f32_16x16x32_bf16 v[46:49], v[158:161], v[182:185], v[46:49]
	v_mfma_f32_16x16x32_bf16 v[38:41], v[166:169], v[182:185], v[38:41]
	v_mfma_f32_16x16x32_bf16 v[30:33], v[158:161], v[190:193], v[30:33]
	v_mfma_f32_16x16x32_bf16 v[22:25], v[166:169], v[190:193], v[22:25]
	v_mfma_f32_16x16x32_bf16 v[14:17], v[158:161], v[198:201], v[14:17]
	v_mfma_f32_16x16x32_bf16 v[2:5], v[166:169], v[198:201], v[2:5]
	v_mfma_f32_16x16x32_bf16 v[62:65], v[162:165], v[178:181], v[62:65]
	v_mfma_f32_16x16x32_bf16 v[54:57], v[170:173], v[178:181], v[54:57]
	v_mfma_f32_16x16x32_bf16 v[46:49], v[162:165], v[186:189], v[46:49]
	v_mfma_f32_16x16x32_bf16 v[38:41], v[170:173], v[186:189], v[38:41]
	v_mfma_f32_16x16x32_bf16 v[30:33], v[162:165], v[194:197], v[30:33]
	v_mfma_f32_16x16x32_bf16 v[22:25], v[170:173], v[194:197], v[22:25]
	v_mfma_f32_16x16x32_bf16 v[14:17], v[162:165], v[202:205], v[14:17]
	v_mfma_f32_16x16x32_bf16 v[2:5], v[170:173], v[202:205], v[2:5]
	s_barrier
	s_add_i32 s88, s88, 2
	s_add_u32 s86, s86, 0x100
	s_addc_u32 s87, s87, 0
	s_cmp_gt_u32 s88, 13
	s_mov_b64 s[42:43], s[0:1]
	s_cbranch_scc0 .LBB0_800
	s_and_b64 vcc, exec, s[8:9]
	s_cbranch_vccz .LBB0_803
	s_barrier

.LBB0_1068:
	v_add_u32_e32 v16, s0, v246
	ds_read_b64_tr_b16 v[6:7], v16 offset:49664
	ds_read_b64_tr_b16 v[4:5], v16 offset:49152
	ds_read_b128 v[12:15], v244
	s_add_i32 s0, s35, -2
	s_min_i32 s0, s0, s91
	s_ashr_i32 s1, s0, 31
	s_lshl_b64 s[0:1], s[0:1], 17
	s_add_u32 s0, s87, s0
	s_addc_u32 s1, s88, s1
	s_add_i32 s4, s36, s81
	s_mov_b32 m0, s4
	s_nop 4
	global_load_lds_dwordx4 v237, s[0:1]
	s_add_u32 s0, s0, 0x80
	s_addc_u32 s1, s1, 0
	s_add_i32 s4, s36, s82
	s_mov_b32 m0, s4
	s_nop 4
	global_load_lds_dwordx4 v237, s[0:1]
	s_add_i32 s0, s35, -4
	s_min_i32 s0, s0, s91
	s_ashr_i32 s1, s0, 31
	s_lshl_b64 s[0:1], s[0:1], 17
	s_add_u32 s0, s89, s0
	s_addc_u32 s1, s90, s1
	s_add_i32 s4, s34, s80
	s_mov_b32 m0, s4
	s_nop 4
	global_load_lds_dwordx4 v238, s[0:1]
	s_add_u32 s0, s0, 0x80
	s_addc_u32 s1, s1, 0
	s_add_i32 s4, s34, s84
	s_mov_b32 m0, s4
	s_nop 4
	global_load_lds_dwordx4 v238, s[0:1]
	s_waitcnt lgkmcnt(0)
	v_mfma_f32_32x32x16_bf16 v[146:161], v[206:209], v[12:15], v[82:97]
	v_add_f32_e32 v2, v114, v115
	v_add_f32_e32 v2, v116, v2
	v_add_f32_e32 v2, v117, v2
	v_add_f32_e32 v2, v118, v2
	v_add_f32_e32 v2, v119, v2
	v_cvt_pk_bf16_f32 v174, v114, v115
	v_cvt_pk_bf16_f32 v175, v116, v117
	ds_read_b64_tr_b16 v[10:11], v16 offset:53760
	ds_read_b64_tr_b16 v[8:9], v16 offset:53248
	ds_read_b128 v[206:209], v244 offset:1024
	v_mfma_f32_32x32x16_bf16 v[130:145], v[202:205], v[12:15], v[82:97]
	v_add_f32_e32 v2, v120, v2
	v_add_f32_e32 v2, v121, v2
	v_add_f32_e32 v2, v122, v2
	v_add_f32_e32 v2, v123, v2
	v_cvt_pk_bf16_f32 v176, v118, v119
	v_cvt_pk_bf16_f32 v177, v120, v121
	ds_read_b64_tr_b16 v[12:13], v16 offset:50176
	ds_read_b64_tr_b16 v[14:15], v16 offset:50688
	s_waitcnt lgkmcnt(2)
	v_mfma_f32_32x32x16_bf16 v[146:161], v[198:201], v[206:209], v[146:161]
	v_add_f32_e32 v2, v124, v2
	v_add_f32_e32 v2, v125, v2
	v_add_f32_e32 v2, v126, v2
	v_add_f32_e32 v2, v127, v2
	v_cvt_pk_bf16_f32 v170, v122, v123
	v_cvt_pk_bf16_f32 v171, v124, v125
	ds_read_b64_tr_b16 v[116:117], v16 offset:54784
	ds_read_b64_tr_b16 v[114:115], v16 offset:54272
	ds_read_b128 v[122:125], v244 offset:2048
	v_mfma_f32_32x32x16_bf16 v[130:145], v[194:197], v[206:209], v[130:145]
	v_add_f32_e32 v2, v128, v2
	v_add_f32_e32 v2, v129, v2
	v_add_f32_e32 v2, v98, v2
	v_add_f32_e32 v2, v99, v2
	v_cvt_pk_bf16_f32 v172, v126, v127
	v_cvt_pk_bf16_f32 v173, v128, v129
	ds_read_b64_tr_b16 v[118:119], v16 offset:51200
	ds_read_b64_tr_b16 v[120:121], v16 offset:51712
	s_waitcnt lgkmcnt(2)
	v_mfma_f32_32x32x16_bf16 v[146:161], v[190:193], v[122:125], v[146:161]
	v_add_f32_e32 v2, v100, v2
	v_add_f32_e32 v2, v101, v2
	v_add_f32_e32 v2, v102, v2
	v_add_f32_e32 v2, v103, v2
	v_cvt_pk_bf16_f32 v166, v98, v99
	v_cvt_pk_bf16_f32 v167, v100, v101
	ds_read_b64_tr_b16 v[100:101], v16 offset:55808
	ds_read_b64_tr_b16 v[98:99], v16 offset:55296
	ds_read_b128 v[126:129], v244 offset:3072
	v_mfma_f32_32x32x16_bf16 v[130:145], v[186:189], v[122:125], v[130:145]
	v_add_f32_e32 v2, v104, v2
	v_add_f32_e32 v2, v105, v2
	v_add_f32_e32 v2, v106, v2
	v_add_f32_e32 v2, v107, v2
	v_cvt_pk_bf16_f32 v168, v102, v103
	v_cvt_pk_bf16_f32 v169, v104, v105
	ds_read_b64_tr_b16 v[102:103], v16 offset:52224
	ds_read_b64_tr_b16 v[104:105], v16 offset:52736
	s_waitcnt lgkmcnt(2)
	v_mfma_f32_32x32x16_bf16 v[146:161], v[182:185], v[126:129], v[146:161]
	v_add_f32_e32 v2, v108, v2
	v_add_f32_e32 v2, v109, v2
	v_add_f32_e32 v2, v110, v2
	v_add_f32_e32 v2, v111, v2
	v_cvt_pk_bf16_f32 v162, v106, v107
	v_cvt_pk_bf16_f32 v163, v108, v109
	ds_read_b64_tr_b16 v[106:107], v16 offset:56320
	ds_read_b64_tr_b16 v[108:109], v16 offset:56832
	v_mfma_f32_32x32x16_bf16 v[130:145], v[178:181], v[126:129], v[130:145]
	v_add_f32_e32 v2, v112, v2
	v_add_f32_e32 v2, v113, v2
	v_add_f32_e32 v2, 0, v2
	v_cvt_pk_bf16_f32 v164, v110, v111
	v_cvt_pk_bf16_f32 v165, v112, v113
	s_nop 0
	v_max_f32_e32 v17, v147, v147
	v_max_f32_e32 v110, v146, v146
	s_nop 0
	v_max_f32_e32 v17, v110, v17
	s_nop 0
	s_nop 0
	v_max3_f32 v110, v148, v149, v131
	v_max3_f32 v17, v17, v130, v132
	v_max3_f32 v17, v17, v133, v150
	v_max3_f32 v110, v110, v152, v153
	v_max3_f32 v17, v17, v151, v134
	v_max3_f32 v110, v110, v136, v137
	v_max3_f32 v17, v17, v135, v154
	v_max3_f32 v110, v110, v156, v157
	v_max3_f32 v17, v17, v155, v138
	v_max3_f32 v110, v110, v140, v141
	v_max3_f32 v17, v17, v139, v158
	v_max3_f32 v110, v110, v160, v161
	v_max3_f32 v17, v17, v159, v142
	v_max3_f32 v110, v110, v144, v145
	v_max3_f32 v17, v17, v143, v110
	v_mov_b32_e32 v110, v17
	s_nop 0
	s_nop 0
	v_permlane32_swap_b32_e32 v17, v110
	v_max_f32_e32 v110, v110, v110
	v_max_f32_e32 v17, v17, v17
	v_max_f32_e32 v17, v17, v110
	v_cmp_lt_f32_e32 vcc, s62, v17
	s_cmp_lg_u64 vcc, 0
	v_add_f32_e32 v2, v248, v2
	s_cselect_b64 s[0:1], -1, 0
	s_cbranch_vccnz .LBB0_1076

.LBB0_1071:
	s_add_i32 s0, s34, 0x4000
	s_cmpk_lg_u32 s34, 0x8000
	s_cselect_b32 s92, s0, 0
	v_add_u32_e32 v16, s36, v246
	ds_read_b64_tr_b16 v[180:181], v16 offset:49664
	ds_read_b64_tr_b16 v[178:179], v16 offset:49152
	ds_read_b128 v[198:201], v244
	s_add_i32 s0, s35, -1
	s_min_i32 s0, s0, s91
	s_ashr_i32 s1, s0, 31
	s_lshl_b64 s[0:1], s[0:1], 17
	s_add_u32 s0, s87, s0
	s_addc_u32 s1, s88, s1
	s_add_i32 s4, s34, s81
	s_mov_b32 m0, s4
	s_nop 4
	global_load_lds_dwordx4 v237, s[0:1]
	s_add_u32 s0, s0, 0x80
	s_addc_u32 s1, s1, 0
	s_add_i32 s93, s35, -3
	s_add_i32 s4, s34, s82
	s_mov_b32 m0, s4
	s_nop 4
	global_load_lds_dwordx4 v237, s[0:1]
	s_min_i32 s0, s93, s91
	s_ashr_i32 s1, s0, 31
	s_lshl_b64 s[0:1], s[0:1], 17
	s_add_u32 s0, s89, s0
	s_addc_u32 s1, s90, s1
	s_add_i32 s4, s92, s80
	s_mov_b32 m0, s4
	s_nop 4
	global_load_lds_dwordx4 v238, s[0:1]
	s_add_u32 s0, s0, 0x80
	s_addc_u32 s1, s1, 0
	s_add_i32 s4, s92, s84
	s_mov_b32 m0, s4
	s_nop 4
	global_load_lds_dwordx4 v238, s[0:1]
	s_waitcnt lgkmcnt(0)
	v_mfma_f32_32x32x16_bf16 v[114:129], v[98:101], v[198:201], v[82:97]
	v_add_f32_e32 v17, v146, v147
	v_add_f32_e32 v17, v148, v17
	v_add_f32_e32 v17, v149, v17
	v_add_f32_e32 v17, v150, v17
	v_add_f32_e32 v17, v151, v17
	v_cvt_pk_bf16_f32 v174, v146, v147
	v_cvt_pk_bf16_f32 v175, v148, v149
	ds_read_b64_tr_b16 v[148:149], v16 offset:53760
	ds_read_b64_tr_b16 v[146:147], v16 offset:53248
	ds_read_b128 v[202:205], v244 offset:1024
	v_mfma_f32_32x32x16_bf16 v[98:113], v[194:197], v[198:201], v[82:97]
	v_add_f32_e32 v17, v152, v17
	v_add_f32_e32 v17, v153, v17
	v_add_f32_e32 v17, v154, v17
	v_add_f32_e32 v17, v155, v17
	v_cvt_pk_bf16_f32 v176, v150, v151
	v_cvt_pk_bf16_f32 v177, v152, v153
	ds_read_b64_tr_b16 v[150:151], v16 offset:50176
	ds_read_b64_tr_b16 v[152:153], v16 offset:50688
	s_waitcnt lgkmcnt(2)
	v_mfma_f32_32x32x16_bf16 v[114:129], v[190:193], v[202:205], v[114:129]
	v_add_f32_e32 v17, v156, v17
	v_add_f32_e32 v17, v157, v17
	v_add_f32_e32 v17, v158, v17
	v_add_f32_e32 v17, v159, v17
	v_cvt_pk_bf16_f32 v170, v154, v155
	v_cvt_pk_bf16_f32 v171, v156, v157
	ds_read_b64_tr_b16 v[156:157], v16 offset:54784
	ds_read_b64_tr_b16 v[154:155], v16 offset:54272
	ds_read_b128 v[190:193], v244 offset:2048
	v_mfma_f32_32x32x16_bf16 v[98:113], v[186:189], v[202:205], v[98:113]
	v_add_f32_e32 v17, v160, v17
	v_add_f32_e32 v17, v161, v17
	v_add_f32_e32 v17, v130, v17
	v_add_f32_e32 v17, v131, v17
	v_cvt_pk_bf16_f32 v172, v158, v159
	v_cvt_pk_bf16_f32 v173, v160, v161
	ds_read_b64_tr_b16 v[158:159], v16 offset:51200
	ds_read_b64_tr_b16 v[160:161], v16 offset:51712
	s_waitcnt lgkmcnt(2)
	v_mfma_f32_32x32x16_bf16 v[114:129], v[182:185], v[190:193], v[114:129]
	v_add_f32_e32 v17, v132, v17
	v_add_f32_e32 v17, v133, v17
	v_add_f32_e32 v17, v134, v17
	v_add_f32_e32 v17, v135, v17
	v_cvt_pk_bf16_f32 v166, v130, v131
	v_cvt_pk_bf16_f32 v167, v132, v133
	ds_read_b64_tr_b16 v[132:133], v16 offset:55808
	ds_read_b64_tr_b16 v[130:131], v16 offset:55296
	ds_read_b128 v[182:185], v244 offset:3072
	v_mfma_f32_32x32x16_bf16 v[98:113], v[12:15], v[190:193], v[98:113]
	v_add_f32_e32 v17, v136, v17
	v_add_f32_e32 v17, v137, v17
	v_add_f32_e32 v17, v138, v17
	v_add_f32_e32 v17, v139, v17
	v_cvt_pk_bf16_f32 v168, v134, v135
	v_cvt_pk_bf16_f32 v169, v136, v137
	ds_read_b64_tr_b16 v[12:13], v16 offset:52224
	ds_read_b64_tr_b16 v[14:15], v16 offset:52736
	s_waitcnt lgkmcnt(2)
	v_mfma_f32_32x32x16_bf16 v[114:129], v[8:11], v[182:185], v[114:129]
	v_add_f32_e32 v17, v140, v17
	v_add_f32_e32 v17, v141, v17
	v_add_f32_e32 v17, v142, v17
	v_add_f32_e32 v17, v143, v17
	v_cvt_pk_bf16_f32 v162, v138, v139
	v_cvt_pk_bf16_f32 v163, v140, v141
	ds_read_b64_tr_b16 v[8:9], v16 offset:56320
	ds_read_b64_tr_b16 v[10:11], v16 offset:56832
	v_mfma_f32_32x32x16_bf16 v[98:113], v[4:7], v[182:185], v[98:113]
	v_add_f32_e32 v17, v144, v17
	v_add_f32_e32 v17, v145, v17
	v_add_f32_e32 v17, 0, v17
	v_cvt_pk_bf16_f32 v164, v142, v143
	v_cvt_pk_bf16_f32 v165, v144, v145
	s_nop 0
	v_max_f32_e32 v4, v115, v115
	v_max_f32_e32 v5, v114, v114
	s_nop 0
	v_max_f32_e32 v4, v5, v4
	s_nop 0
	s_nop 0
	v_max3_f32 v5, v116, v117, v99
	v_max3_f32 v4, v4, v98, v100
	v_max3_f32 v4, v4, v101, v118
	v_max3_f32 v5, v5, v120, v121
	v_max3_f32 v4, v4, v119, v102
	v_max3_f32 v5, v5, v104, v105
	v_max3_f32 v4, v4, v103, v122
	v_max3_f32 v5, v5, v124, v125
	v_max3_f32 v4, v4, v123, v106
	v_max3_f32 v5, v5, v108, v109
	v_max3_f32 v4, v4, v107, v126
	v_max3_f32 v5, v5, v128, v129
	v_max3_f32 v4, v4, v127, v110
	v_max3_f32 v5, v5, v112, v113
	v_add_f32_e32 v248, v2, v17
	v_max3_f32 v2, v4, v111, v5
	v_mov_b32_e32 v4, v2
	s_nop 0
	s_nop 0
	v_permlane32_swap_b32_e32 v2, v4
	v_max_f32_e32 v4, v4, v4
	v_max_f32_e32 v2, v2, v2
	v_max_f32_e32 v2, v2, v4
	v_cmp_lt_f32_e32 vcc, s62, v2
	s_cmp_lg_u64 vcc, 0
	s_cselect_b64 s[0:1], -1, 0
	s_cbranch_vccnz .LBB0_1079

.LBB0_1144:
	v_add_u32_e32 v185, s0, v201
	ds_read_b64_tr_b16 v[180:181], v185 offset:49152
	ds_read_b64_tr_b16 v[182:183], v185 offset:49664
	s_add_u32 s79, s22, s4
	s_addc_u32 s80, s23, s5
	s_add_u32 s0, s79, 0x80000
	s_addc_u32 s1, s80, 0
	s_add_i32 s12, s73, s34
	s_mov_b32 m0, s12
	s_nop 4
	global_load_lds_dwordx4 v203, s[0:1]
	s_add_u32 s0, s79, 0x80080
	s_addc_u32 s1, s80, 0
	s_add_i32 s12, s73, s35
	s_add_u32 s81, s24, s4
	s_addc_u32 s82, s25, s5
	s_mov_b32 m0, s12
	s_nop 4
	global_load_lds_dwordx4 v203, s[0:1]
	s_add_u32 s0, s81, 0x40000
	s_addc_u32 s1, s82, 0
	s_add_i32 s12, s67, s39
	s_mov_b32 m0, s12
	s_nop 4
	global_load_lds_dwordx4 v200, s[0:1]
	s_add_u32 s0, s81, 0x40080
	s_addc_u32 s1, s82, 0
	s_add_i32 s12, s67, s64
	s_mov_b32 m0, s12
	s_nop 4
	global_load_lds_dwordx4 v200, s[0:1]
	s_waitcnt lgkmcnt(9)
	v_mfma_f32_32x32x16_bf16 v[100:115], v[84:87], v[160:163], v[36:51]
	v_add_f32_e32 v88, v68, v69
	v_add_f32_e32 v88, v70, v88
	v_add_f32_e32 v88, v71, v88
	v_add_f32_e32 v88, v72, v88
	v_add_f32_e32 v88, v73, v88
	v_cvt_pk_bf16_f32 v144, v68, v69
	v_cvt_pk_bf16_f32 v145, v70, v71
	ds_read_b64_tr_b16 v[176:177], v185 offset:53248
	ds_read_b64_tr_b16 v[178:179], v185 offset:53760
	v_add_f32_e32 v68, v74, v88
	s_waitcnt lgkmcnt(10)
	v_mfma_f32_32x32x16_bf16 v[84:99], v[172:175], v[160:163], v[36:51]
	v_add_f32_e32 v68, v75, v68
	v_add_f32_e32 v68, v76, v68
	v_add_f32_e32 v68, v77, v68
	v_cvt_pk_bf16_f32 v146, v72, v73
	v_cvt_pk_bf16_f32 v147, v74, v75
	ds_read_b64_tr_b16 v[172:173], v185 offset:50176
	ds_read_b64_tr_b16 v[174:175], v185 offset:50688
	s_waitcnt lgkmcnt(11)
	v_mfma_f32_32x32x16_bf16 v[100:115], v[168:171], v[156:159], v[100:115]
	v_add_f32_e32 v68, v78, v68
	v_add_f32_e32 v68, v79, v68
	v_add_f32_e32 v68, v80, v68
	v_add_f32_e32 v68, v81, v68
	v_cvt_pk_bf16_f32 v140, v76, v77
	v_cvt_pk_bf16_f32 v141, v78, v79
	ds_read_b64_tr_b16 v[76:77], v185 offset:54272
	ds_read_b64_tr_b16 v[78:79], v185 offset:54784
	s_waitcnt lgkmcnt(12)
	v_mfma_f32_32x32x16_bf16 v[84:99], v[164:167], v[156:159], v[84:99]
	v_add_f32_e32 v68, v82, v68
	v_add_f32_e32 v68, v83, v68
	v_add_f32_e32 v68, v52, v68
	v_add_f32_e32 v68, v53, v68
	v_cvt_pk_bf16_f32 v142, v80, v81
	v_cvt_pk_bf16_f32 v143, v82, v83
	ds_read_b64_tr_b16 v[72:73], v185 offset:51200
	ds_read_b64_tr_b16 v[74:75], v185 offset:51712
	s_waitcnt lgkmcnt(13)
	v_mfma_f32_32x32x16_bf16 v[100:115], v[128:131], v[152:155], v[100:115]
	v_add_f32_e32 v68, v54, v68
	v_add_f32_e32 v68, v55, v68
	v_add_f32_e32 v68, v56, v68
	v_add_f32_e32 v80, v57, v68
	v_cvt_pk_bf16_f32 v136, v52, v53
	v_cvt_pk_bf16_f32 v137, v54, v55
	ds_read_b64_tr_b16 v[68:69], v185 offset:55296
	ds_read_b64_tr_b16 v[70:71], v185 offset:55808
	s_waitcnt lgkmcnt(14)
	v_mfma_f32_32x32x16_bf16 v[84:99], v[124:127], v[152:155], v[84:99]
	v_add_f32_e32 v52, v58, v80
	v_add_f32_e32 v52, v59, v52
	v_add_f32_e32 v52, v60, v52
	v_add_f32_e32 v52, v61, v52
	v_cvt_pk_bf16_f32 v138, v56, v57
	v_cvt_pk_bf16_f32 v139, v58, v59
	ds_read_b64_tr_b16 v[56:57], v185 offset:52224
	ds_read_b64_tr_b16 v[58:59], v185 offset:52736
	s_waitcnt lgkmcnt(14)
	v_mfma_f32_32x32x16_bf16 v[100:115], v[120:123], v[148:151], v[100:115]
	v_add_f32_e32 v52, v62, v52
	v_add_f32_e32 v52, v63, v52
	v_add_f32_e32 v52, v64, v52
	v_add_f32_e32 v80, v65, v52
	v_cvt_pk_bf16_f32 v132, v60, v61
	v_cvt_pk_bf16_f32 v133, v62, v63
	ds_read_b64_tr_b16 v[52:53], v185 offset:56320
	ds_read_b64_tr_b16 v[54:55], v185 offset:56832
	v_mfma_f32_32x32x16_bf16 v[84:99], v[116:119], v[148:151], v[84:99]
	v_add_f32_e32 v60, v66, v80
	v_add_f32_e32 v60, v67, v60
	v_add_f32_e32 v60, 0, v60
	v_cvt_pk_bf16_f32 v134, v64, v65
	v_cvt_pk_bf16_f32 v135, v66, v67
	v_max_f32_e32 v61, v101, v101
	v_max_f32_e32 v62, v100, v100
	v_max_f32_e32 v61, v62, v61
	s_nop 3
	v_max3_f32 v62, v102, v103, v85
	v_max3_f32 v61, v61, v84, v86
	v_max3_f32 v61, v61, v87, v104
	v_max3_f32 v62, v62, v106, v107
	v_max3_f32 v61, v61, v105, v88
	v_max3_f32 v62, v62, v90, v91
	v_max3_f32 v61, v61, v89, v108
	v_max3_f32 v62, v62, v110, v111
	v_max3_f32 v61, v61, v109, v92
	v_max3_f32 v62, v62, v94, v95
	v_max3_f32 v61, v61, v93, v112
	v_max3_f32 v62, v62, v114, v115
	v_max3_f32 v61, v61, v113, v96
	v_max3_f32 v62, v62, v98, v99
	v_add_f32_e32 v188, v184, v60
	v_max3_f32 v60, v61, v97, v62
	v_mov_b32_e32 v61, v60
	s_nop 0
	s_nop 0
	v_permlane32_swap_b32_e32 v60, v61
	v_max_f32_e32 v61, v61, v61
	v_max_f32_e32 v60, v60, v60
	v_max_f32_e32 v60, v60, v61
	v_cmp_lt_f32_e32 vcc, s62, v60
	s_cmp_lg_u64 vcc, 0
	s_cselect_b64 s[0:1], -1, 0
	s_cbranch_vccnz .LBB0_1152

.LBB0_1147:
	s_add_i32 s0, s67, 0x4000
	s_cmpk_lg_u32 s67, 0x8000
	s_cselect_b32 s78, s0, 0
	v_add_u32_e32 v189, s73, v201
	ds_read_b64_tr_b16 v[128:129], v189 offset:49152
	ds_read_b64_tr_b16 v[130:131], v189 offset:49664
	s_add_u32 s0, s79, 0xa0000
	s_addc_u32 s1, s80, 0
	s_add_i32 s12, s67, s34
	s_mov_b32 m0, s12
	s_nop 4
	global_load_lds_dwordx4 v203, s[0:1]
	s_add_u32 s0, s79, 0xa0080
	s_addc_u32 s1, s80, 0
	s_add_i32 s12, s67, s35
	s_mov_b32 m0, s12
	s_nop 4
	global_load_lds_dwordx4 v203, s[0:1]
	s_add_u32 s0, s81, 0x60000
	s_addc_u32 s1, s82, 0
	s_add_i32 s12, s78, s39
	s_mov_b32 m0, s12
	s_nop 4
	global_load_lds_dwordx4 v200, s[0:1]
	s_add_u32 s0, s81, 0x60080
	s_addc_u32 s1, s82, 0
	s_add_i32 s12, s78, s64
	s_mov_b32 m0, s12
	s_nop 4
	global_load_lds_dwordx4 v200, s[0:1]
	s_waitcnt lgkmcnt(9)
	v_mfma_f32_32x32x16_bf16 v[68:83], v[60:63], v[160:163], v[36:51]
	v_add_f32_e32 v52, v100, v101
	v_add_f32_e32 v52, v102, v52
	v_add_f32_e32 v52, v103, v52
	v_add_f32_e32 v52, v104, v52
	v_add_f32_e32 v52, v105, v52
	v_cvt_pk_bf16_f32 v144, v100, v101
	v_cvt_pk_bf16_f32 v145, v102, v103
	ds_read_b64_tr_b16 v[124:125], v189 offset:53248
	ds_read_b64_tr_b16 v[126:127], v189 offset:53760
	v_add_f32_e32 v52, v106, v52
	v_add_f32_e32 v52, v107, v52
	v_add_f32_e32 v52, v108, v52
	v_add_f32_e32 v100, v109, v52
	s_waitcnt lgkmcnt(10)
	v_mfma_f32_32x32x16_bf16 v[52:67], v[116:119], v[160:163], v[36:51]
	v_cvt_pk_bf16_f32 v146, v104, v105
	v_cvt_pk_bf16_f32 v147, v106, v107
	ds_read_b64_tr_b16 v[120:121], v189 offset:50176
	ds_read_b64_tr_b16 v[122:123], v189 offset:50688
	s_waitcnt lgkmcnt(11)
	v_mfma_f32_32x32x16_bf16 v[68:83], v[184:187], v[156:159], v[68:83]
	v_add_f32_e32 v100, v110, v100
	v_add_f32_e32 v100, v111, v100
	v_add_f32_e32 v100, v112, v100
	v_add_f32_e32 v100, v113, v100
	v_cvt_pk_bf16_f32 v140, v108, v109
	v_cvt_pk_bf16_f32 v141, v110, v111
	ds_read_b64_tr_b16 v[116:117], v189 offset:54272
	ds_read_b64_tr_b16 v[118:119], v189 offset:54784
	s_waitcnt lgkmcnt(12)
	v_mfma_f32_32x32x16_bf16 v[52:67], v[176:179], v[156:159], v[52:67]
	v_add_f32_e32 v100, v114, v100
	v_add_f32_e32 v100, v115, v100
	v_add_f32_e32 v100, v84, v100
	v_add_f32_e32 v100, v85, v100
	v_cvt_pk_bf16_f32 v142, v112, v113
	v_cvt_pk_bf16_f32 v143, v114, v115
	ds_read_b64_tr_b16 v[108:109], v189 offset:51200
	ds_read_b64_tr_b16 v[110:111], v189 offset:51712
	s_waitcnt lgkmcnt(13)
	v_mfma_f32_32x32x16_bf16 v[68:83], v[180:183], v[152:155], v[68:83]
	v_add_f32_e32 v100, v86, v100
	v_add_f32_e32 v100, v87, v100
	v_add_f32_e32 v100, v88, v100
	v_add_f32_e32 v100, v89, v100
	v_cvt_pk_bf16_f32 v136, v84, v85
	v_cvt_pk_bf16_f32 v137, v86, v87
	ds_read_b64_tr_b16 v[104:105], v189 offset:55296
	ds_read_b64_tr_b16 v[106:107], v189 offset:55808
	s_waitcnt lgkmcnt(14)
	v_mfma_f32_32x32x16_bf16 v[52:67], v[168:171], v[152:155], v[52:67]
	v_add_f32_e32 v84, v90, v100
	v_add_f32_e32 v84, v91, v84
	v_add_f32_e32 v84, v92, v84
	v_add_f32_e32 v84, v93, v84
	v_cvt_pk_bf16_f32 v138, v88, v89
	v_cvt_pk_bf16_f32 v139, v90, v91
	ds_read_b64_tr_b16 v[100:101], v189 offset:52224
	ds_read_b64_tr_b16 v[102:103], v189 offset:52736
	s_waitcnt lgkmcnt(14)
	v_mfma_f32_32x32x16_bf16 v[68:83], v[172:175], v[148:151], v[68:83]
	v_add_f32_e32 v84, v94, v84
	v_add_f32_e32 v84, v95, v84
	v_add_f32_e32 v84, v96, v84
	v_add_f32_e32 v84, v97, v84
	v_cvt_pk_bf16_f32 v132, v92, v93
	v_cvt_pk_bf16_f32 v133, v94, v95
	ds_read_b64_tr_b16 v[88:89], v189 offset:56320
	ds_read_b64_tr_b16 v[90:91], v189 offset:56832
	v_mfma_f32_32x32x16_bf16 v[52:67], v[164:167], v[148:151], v[52:67]
	v_add_f32_e32 v84, v98, v84
	v_add_f32_e32 v84, v99, v84
	v_add_f32_e32 v84, 0, v84
	v_cvt_pk_bf16_f32 v134, v96, v97
	v_cvt_pk_bf16_f32 v135, v98, v99
	v_max_f32_e32 v85, v69, v69
	v_max_f32_e32 v86, v68, v68
	v_max_f32_e32 v85, v86, v85
	s_nop 3
	v_max3_f32 v86, v70, v71, v53
	v_max3_f32 v85, v85, v52, v54
	v_max3_f32 v85, v85, v55, v72
	v_max3_f32 v86, v86, v74, v75
	v_max3_f32 v85, v85, v73, v56
	v_max3_f32 v86, v86, v58, v59
	v_max3_f32 v85, v85, v57, v76
	v_max3_f32 v86, v86, v78, v79
	v_max3_f32 v85, v85, v77, v60
	v_max3_f32 v86, v86, v62, v63
	v_max3_f32 v85, v85, v61, v80
	v_max3_f32 v86, v86, v82, v83
	v_max3_f32 v85, v85, v81, v64
	v_max3_f32 v86, v86, v66, v67
	v_add_f32_e32 v184, v188, v84
	v_max3_f32 v84, v85, v65, v86
	v_mov_b32_e32 v85, v84
	s_nop 0
	s_nop 0
	v_permlane32_swap_b32_e32 v84, v85
	v_max_f32_e32 v85, v85, v85
	v_max_f32_e32 v84, v84, v84
	v_max_f32_e32 v84, v84, v85
	v_cmp_lt_f32_e32 vcc, s62, v84
	s_cmp_lg_u64 vcc, 0
	s_cselect_b64 s[0:1], -1, 0
	s_cbranch_vccnz .LBB0_1155

.Lwd_3_0:
	s_waitcnt lgkmcnt(0)
	s_barrier
	s_waitcnt lgkmcnt(7)
	v_mfma_f32_16x16x32_bf16 v[122:125], v[142:145], v[174:177], v[122:125]
	v_mfma_f32_16x16x32_bf16 v[114:117], v[150:153], v[174:177], v[114:117]
	s_waitcnt lgkmcnt(5)
	v_mfma_f32_16x16x32_bf16 v[106:109], v[142:145], v[182:185], v[106:109]
	v_mfma_f32_16x16x32_bf16 v[98:101], v[150:153], v[182:185], v[98:101]
	s_waitcnt lgkmcnt(3)
	v_mfma_f32_16x16x32_bf16 v[90:93], v[142:145], v[190:193], v[90:93]
	v_mfma_f32_16x16x32_bf16 v[82:85], v[150:153], v[190:193], v[82:85]
	s_waitcnt lgkmcnt(1)
	v_mfma_f32_16x16x32_bf16 v[74:77], v[142:145], v[198:201], v[74:77]
	v_mfma_f32_16x16x32_bf16 v[66:69], v[150:153], v[198:201], v[66:69]
	v_mfma_f32_16x16x32_bf16 v[122:125], v[146:149], v[178:181], v[122:125]
	v_mfma_f32_16x16x32_bf16 v[114:117], v[154:157], v[178:181], v[114:117]
	v_mfma_f32_16x16x32_bf16 v[106:109], v[146:149], v[186:189], v[106:109]
	v_mfma_f32_16x16x32_bf16 v[98:101], v[154:157], v[186:189], v[98:101]
	v_mfma_f32_16x16x32_bf16 v[90:93], v[146:149], v[194:197], v[90:93]
	v_mfma_f32_16x16x32_bf16 v[82:85], v[154:157], v[194:197], v[82:85]
	s_waitcnt lgkmcnt(0)
	v_mfma_f32_16x16x32_bf16 v[74:77], v[146:149], v[202:205], v[74:77]
	v_mfma_f32_16x16x32_bf16 v[66:69], v[154:157], v[202:205], v[66:69]
	v_mfma_f32_16x16x32_bf16 v[126:129], v[158:161], v[174:177], v[126:129]
	v_mfma_f32_16x16x32_bf16 v[118:121], v[166:169], v[174:177], v[118:121]
	v_mfma_f32_16x16x32_bf16 v[110:113], v[158:161], v[182:185], v[110:113]
	v_mfma_f32_16x16x32_bf16 v[102:105], v[166:169], v[182:185], v[102:105]
	v_mfma_f32_16x16x32_bf16 v[94:97], v[158:161], v[190:193], v[94:97]
	v_mfma_f32_16x16x32_bf16 v[86:89], v[166:169], v[190:193], v[86:89]
	v_mfma_f32_16x16x32_bf16 v[78:81], v[158:161], v[198:201], v[78:81]
	v_mfma_f32_16x16x32_bf16 v[70:73], v[166:169], v[198:201], v[70:73]
	v_mfma_f32_16x16x32_bf16 v[126:129], v[162:165], v[178:181], v[126:129]
	v_mfma_f32_16x16x32_bf16 v[118:121], v[170:173], v[178:181], v[118:121]
	v_mfma_f32_16x16x32_bf16 v[110:113], v[162:165], v[186:189], v[110:113]
	v_mfma_f32_16x16x32_bf16 v[102:105], v[170:173], v[186:189], v[102:105]
	v_mfma_f32_16x16x32_bf16 v[94:97], v[162:165], v[194:197], v[94:97]
	v_mfma_f32_16x16x32_bf16 v[86:89], v[170:173], v[194:197], v[86:89]
	v_mfma_f32_16x16x32_bf16 v[78:81], v[162:165], v[202:205], v[78:81]
	v_mfma_f32_16x16x32_bf16 v[70:73], v[170:173], v[202:205], v[70:73]
	s_barrier
	ds_read_b128 v[174:177], v140 offset:16384
	ds_read_b128 v[178:181], v140 offset:17408
	ds_read_b128 v[182:185], v140 offset:18432
	ds_read_b128 v[186:189], v140 offset:19456
	ds_read_b128 v[190:193], v140 offset:20480
	ds_read_b128 v[194:197], v140 offset:21504
	ds_read_b128 v[198:201], v140 offset:22528
	ds_read_b128 v[202:205], v140 offset:23552
	s_mov_b32 s12, m0
	s_mov_b32 m0, s46
	s_nop 4
	global_load_lds_dwordx4 v136, s[40:41]
	s_mov_b32 m0, s12
	s_add_u32 s12, s40, 0x20000
	s_addc_u32 s13, s41, 0
	s_mov_b32 s36, m0
	s_mov_b32 m0, s47
	s_nop 4
	global_load_lds_dwordx4 v136, s[12:13]
	s_mov_b32 m0, s36
	s_add_u32 s12, s40, 0x40000
	s_addc_u32 s13, s41, 0
	s_mov_b32 s36, m0
	s_mov_b32 m0, s48
	s_nop 4
	global_load_lds_dwordx4 v136, s[12:13]
	s_mov_b32 m0, s36
	s_add_u32 s12, s40, 0x60000
	s_addc_u32 s13, s41, 0
	s_mov_b32 s36, m0
	s_mov_b32 m0, s49
	s_nop 4
	global_load_lds_dwordx4 v136, s[12:13]
	s_mov_b32 m0, s36
	s_mov_b32 s12, m0
	s_mov_b32 m0, s27
	s_nop 4
	global_load_lds_dwordx4 v1, s[34:35]
	s_mov_b32 m0, s12
	s_add_u32 s12, s34, 0x20000
	s_addc_u32 s13, s35, 0
	s_mov_b32 s36, m0
	s_mov_b32 m0, s50
	s_nop 4
	global_load_lds_dwordx4 v1, s[12:13]
	s_mov_b32 m0, s36
	s_cmp_eq_u32 s66, -2
	s_cselect_b32 s99, s98, 0
	s_cmp_eq_u32 s99, 0
	s_cbranch_scc1 .Lw8_3_1
	s_waitcnt vmcnt(16)
	s_branch .Lwd_3_1

.Lwd_3_1:
	s_waitcnt lgkmcnt(0)
	s_barrier
	s_waitcnt lgkmcnt(7)
	v_mfma_f32_16x16x32_bf16 v[58:61], v[142:145], v[174:177], v[58:61]
	v_mfma_f32_16x16x32_bf16 v[50:53], v[150:153], v[174:177], v[50:53]
	s_waitcnt lgkmcnt(5)
	v_mfma_f32_16x16x32_bf16 v[42:45], v[142:145], v[182:185], v[42:45]
	v_mfma_f32_16x16x32_bf16 v[34:37], v[150:153], v[182:185], v[34:37]
	s_waitcnt lgkmcnt(3)
	v_mfma_f32_16x16x32_bf16 v[26:29], v[142:145], v[190:193], v[26:29]
	v_mfma_f32_16x16x32_bf16 v[18:21], v[150:153], v[190:193], v[18:21]
	s_waitcnt lgkmcnt(1)
	v_mfma_f32_16x16x32_bf16 v[10:13], v[142:145], v[198:201], v[10:13]
	v_mfma_f32_16x16x32_bf16 v[6:9], v[150:153], v[198:201], v[6:9]
	v_mfma_f32_16x16x32_bf16 v[58:61], v[146:149], v[178:181], v[58:61]
	v_mfma_f32_16x16x32_bf16 v[50:53], v[154:157], v[178:181], v[50:53]
	v_mfma_f32_16x16x32_bf16 v[42:45], v[146:149], v[186:189], v[42:45]
	v_mfma_f32_16x16x32_bf16 v[34:37], v[154:157], v[186:189], v[34:37]
	v_mfma_f32_16x16x32_bf16 v[26:29], v[146:149], v[194:197], v[26:29]
	v_mfma_f32_16x16x32_bf16 v[18:21], v[154:157], v[194:197], v[18:21]
	s_waitcnt lgkmcnt(0)
	v_mfma_f32_16x16x32_bf16 v[10:13], v[146:149], v[202:205], v[10:13]
	v_mfma_f32_16x16x32_bf16 v[6:9], v[154:157], v[202:205], v[6:9]
	v_mfma_f32_16x16x32_bf16 v[62:65], v[158:161], v[174:177], v[62:65]
	v_mfma_f32_16x16x32_bf16 v[54:57], v[166:169], v[174:177], v[54:57]
	v_mfma_f32_16x16x32_bf16 v[46:49], v[158:161], v[182:185], v[46:49]
	v_mfma_f32_16x16x32_bf16 v[38:41], v[166:169], v[182:185], v[38:41]
	v_mfma_f32_16x16x32_bf16 v[30:33], v[158:161], v[190:193], v[30:33]
	v_mfma_f32_16x16x32_bf16 v[22:25], v[166:169], v[190:193], v[22:25]
	v_mfma_f32_16x16x32_bf16 v[14:17], v[158:161], v[198:201], v[14:17]
	v_mfma_f32_16x16x32_bf16 v[2:5], v[166:169], v[198:201], v[2:5]
	v_mfma_f32_16x16x32_bf16 v[62:65], v[162:165], v[178:181], v[62:65]
	v_mfma_f32_16x16x32_bf16 v[54:57], v[170:173], v[178:181], v[54:57]
	v_mfma_f32_16x16x32_bf16 v[46:49], v[162:165], v[186:189], v[46:49]
	v_mfma_f32_16x16x32_bf16 v[38:41], v[170:173], v[186:189], v[38:41]
	v_mfma_f32_16x16x32_bf16 v[30:33], v[162:165], v[194:197], v[30:33]
	v_mfma_f32_16x16x32_bf16 v[22:25], v[170:173], v[194:197], v[22:25]
	v_mfma_f32_16x16x32_bf16 v[14:17], v[162:165], v[202:205], v[14:17]
	v_mfma_f32_16x16x32_bf16 v[2:5], v[170:173], v[202:205], v[2:5]
	s_barrier
	v_add_u32_e32 v134, 0x18000, v139
	ds_read_b128 v[142:145], v134
	ds_read_b128 v[146:149], v134 offset:1024
	ds_read_b128 v[150:153], v134 offset:2048
	ds_read_b128 v[154:157], v134 offset:3072
	v_add_u32_e32 v134, 0x1c000, v139
	ds_read_b128 v[158:161], v134
	ds_read_b128 v[162:165], v134 offset:1024
	ds_read_b128 v[166:169], v134 offset:2048
	ds_read_b128 v[170:173], v134 offset:3072
	ds_read_b128 v[174:177], v140 offset:32768
	ds_read_b128 v[178:181], v140 offset:33792
	ds_read_b128 v[182:185], v140 offset:34816
	ds_read_b128 v[186:189], v140 offset:35840
	ds_read_b128 v[190:193], v140 offset:36864
	ds_read_b128 v[194:197], v140 offset:37888
	ds_read_b128 v[198:201], v140 offset:38912
	ds_read_b128 v[202:205], v140 offset:39936
	s_add_u32 s12, s34, 0x40000
	s_addc_u32 s13, s35, 0
	s_mov_b32 s36, m0
	s_mov_b32 m0, s51
	s_nop 4
	global_load_lds_dwordx4 v1, s[12:13]
	s_mov_b32 m0, s36
	s_add_u32 s12, s34, 0x60000
	s_addc_u32 s13, s35, 0
	s_mov_b32 s36, m0
	s_mov_b32 m0, s52
	s_nop 4
	global_load_lds_dwordx4 v1, s[12:13]
	s_mov_b32 m0, s36
	s_waitcnt vmcnt(8)
	s_waitcnt lgkmcnt(0)
	s_barrier
	s_waitcnt lgkmcnt(7)
	v_mfma_f32_16x16x32_bf16 v[122:125], v[142:145], v[174:177], v[122:125]
	v_mfma_f32_16x16x32_bf16 v[114:117], v[150:153], v[174:177], v[114:117]
	s_waitcnt lgkmcnt(5)
	v_mfma_f32_16x16x32_bf16 v[106:109], v[142:145], v[182:185], v[106:109]
	v_mfma_f32_16x16x32_bf16 v[98:101], v[150:153], v[182:185], v[98:101]
	s_waitcnt lgkmcnt(3)
	v_mfma_f32_16x16x32_bf16 v[90:93], v[142:145], v[190:193], v[90:93]
	v_mfma_f32_16x16x32_bf16 v[82:85], v[150:153], v[190:193], v[82:85]
	s_waitcnt lgkmcnt(1)
	v_mfma_f32_16x16x32_bf16 v[74:77], v[142:145], v[198:201], v[74:77]
	v_mfma_f32_16x16x32_bf16 v[66:69], v[150:153], v[198:201], v[66:69]
	v_mfma_f32_16x16x32_bf16 v[122:125], v[146:149], v[178:181], v[122:125]
	v_mfma_f32_16x16x32_bf16 v[114:117], v[154:157], v[178:181], v[114:117]
	v_mfma_f32_16x16x32_bf16 v[106:109], v[146:149], v[186:189], v[106:109]
	v_mfma_f32_16x16x32_bf16 v[98:101], v[154:157], v[186:189], v[98:101]
	v_mfma_f32_16x16x32_bf16 v[90:93], v[146:149], v[194:197], v[90:93]
	v_mfma_f32_16x16x32_bf16 v[82:85], v[154:157], v[194:197], v[82:85]
	s_waitcnt lgkmcnt(0)
	v_mfma_f32_16x16x32_bf16 v[74:77], v[146:149], v[202:205], v[74:77]
	v_mfma_f32_16x16x32_bf16 v[66:69], v[154:157], v[202:205], v[66:69]
	v_mfma_f32_16x16x32_bf16 v[126:129], v[158:161], v[174:177], v[126:129]
	v_mfma_f32_16x16x32_bf16 v[118:121], v[166:169], v[174:177], v[118:121]
	v_mfma_f32_16x16x32_bf16 v[110:113], v[158:161], v[182:185], v[110:113]
	v_mfma_f32_16x16x32_bf16 v[102:105], v[166:169], v[182:185], v[102:105]
	v_mfma_f32_16x16x32_bf16 v[94:97], v[158:161], v[190:193], v[94:97]
	v_mfma_f32_16x16x32_bf16 v[86:89], v[166:169], v[190:193], v[86:89]
	v_mfma_f32_16x16x32_bf16 v[78:81], v[158:161], v[198:201], v[78:81]
	v_mfma_f32_16x16x32_bf16 v[70:73], v[166:169], v[198:201], v[70:73]
	v_mfma_f32_16x16x32_bf16 v[126:129], v[162:165], v[178:181], v[126:129]
	v_mfma_f32_16x16x32_bf16 v[118:121], v[170:173], v[178:181], v[118:121]
	v_mfma_f32_16x16x32_bf16 v[110:113], v[162:165], v[186:189], v[110:113]
	v_mfma_f32_16x16x32_bf16 v[102:105], v[170:173], v[186:189], v[102:105]
	v_mfma_f32_16x16x32_bf16 v[94:97], v[162:165], v[194:197], v[94:97]
	v_mfma_f32_16x16x32_bf16 v[86:89], v[170:173], v[194:197], v[86:89]
	v_mfma_f32_16x16x32_bf16 v[78:81], v[162:165], v[202:205], v[78:81]
	v_mfma_f32_16x16x32_bf16 v[70:73], v[170:173], v[202:205], v[70:73]
	s_barrier
	s_add_u32 s12, s40, 0x80
	s_addc_u32 s13, s41, 0
	ds_read_b128 v[174:177], v140 offset:49152
	ds_read_b128 v[178:181], v140 offset:50176
	ds_read_b128 v[182:185], v140 offset:51200
	ds_read_b128 v[186:189], v140 offset:52224
	ds_read_b128 v[190:193], v140 offset:53248
	ds_read_b128 v[194:197], v140 offset:54272
	ds_read_b128 v[198:201], v140 offset:55296
	ds_read_b128 v[202:205], v140 offset:56320
	s_mov_b32 s36, m0
	s_mov_b32 m0, s53
	s_nop 4
	global_load_lds_dwordx4 v136, s[12:13]
	s_mov_b32 m0, s36
	s_add_u32 s12, s40, 0x20080
	s_addc_u32 s13, s41, 0
	s_mov_b32 s36, m0
	s_mov_b32 m0, s54
	s_nop 4
	global_load_lds_dwordx4 v136, s[12:13]
	s_mov_b32 m0, s36
	s_add_u32 s12, s40, 0x40080
	s_addc_u32 s13, s41, 0
	s_mov_b32 s36, m0
	s_mov_b32 m0, s57
	s_nop 4
	global_load_lds_dwordx4 v136, s[12:13]
	s_mov_b32 m0, s36
	s_add_u32 s12, s40, 0x60080
	s_addc_u32 s13, s41, 0
	s_mov_b32 s36, m0
	s_mov_b32 m0, s58
	s_nop 4
	global_load_lds_dwordx4 v136, s[12:13]
	s_mov_b32 m0, s36
	s_mov_b32 s12, m0
	s_mov_b32 m0, s55
	s_nop 4
	global_load_lds_dwordx4 v1, s[38:39]
	s_mov_b32 m0, s12
	s_add_u32 s12, s34, 0x20080
	s_addc_u32 s13, s35, 0
	s_mov_b32 s34, m0
	s_mov_b32 m0, s56
	s_nop 4
	global_load_lds_dwordx4 v1, s[12:13]
	s_mov_b32 m0, s34
	s_waitcnt vmcnt(8)
	s_waitcnt lgkmcnt(0)
	s_barrier
	s_waitcnt lgkmcnt(7)
	v_mfma_f32_16x16x32_bf16 v[58:61], v[142:145], v[174:177], v[58:61]
	v_mfma_f32_16x16x32_bf16 v[50:53], v[150:153], v[174:177], v[50:53]
	s_waitcnt lgkmcnt(5)
	v_mfma_f32_16x16x32_bf16 v[42:45], v[142:145], v[182:185], v[42:45]
	v_mfma_f32_16x16x32_bf16 v[34:37], v[150:153], v[182:185], v[34:37]
	s_waitcnt lgkmcnt(3)
	v_mfma_f32_16x16x32_bf16 v[26:29], v[142:145], v[190:193], v[26:29]
	v_mfma_f32_16x16x32_bf16 v[18:21], v[150:153], v[190:193], v[18:21]
	s_waitcnt lgkmcnt(1)
	v_mfma_f32_16x16x32_bf16 v[10:13], v[142:145], v[198:201], v[10:13]
	v_mfma_f32_16x16x32_bf16 v[6:9], v[150:153], v[198:201], v[6:9]
	v_mfma_f32_16x16x32_bf16 v[58:61], v[146:149], v[178:181], v[58:61]
	v_mfma_f32_16x16x32_bf16 v[50:53], v[154:157], v[178:181], v[50:53]
	v_mfma_f32_16x16x32_bf16 v[42:45], v[146:149], v[186:189], v[42:45]
	v_mfma_f32_16x16x32_bf16 v[34:37], v[154:157], v[186:189], v[34:37]
	v_mfma_f32_16x16x32_bf16 v[26:29], v[146:149], v[194:197], v[26:29]
	v_mfma_f32_16x16x32_bf16 v[18:21], v[154:157], v[194:197], v[18:21]
	s_waitcnt lgkmcnt(0)
	v_mfma_f32_16x16x32_bf16 v[10:13], v[146:149], v[202:205], v[10:13]
	v_mfma_f32_16x16x32_bf16 v[6:9], v[154:157], v[202:205], v[6:9]
	v_mfma_f32_16x16x32_bf16 v[62:65], v[158:161], v[174:177], v[62:65]
	v_mfma_f32_16x16x32_bf16 v[54:57], v[166:169], v[174:177], v[54:57]
	v_mfma_f32_16x16x32_bf16 v[46:49], v[158:161], v[182:185], v[46:49]
	v_mfma_f32_16x16x32_bf16 v[38:41], v[166:169], v[182:185], v[38:41]
	v_mfma_f32_16x16x32_bf16 v[30:33], v[158:161], v[190:193], v[30:33]
	v_mfma_f32_16x16x32_bf16 v[22:25], v[166:169], v[190:193], v[22:25]
	v_mfma_f32_16x16x32_bf16 v[14:17], v[158:161], v[198:201], v[14:17]
	v_mfma_f32_16x16x32_bf16 v[2:5], v[166:169], v[198:201], v[2:5]
	v_mfma_f32_16x16x32_bf16 v[62:65], v[162:165], v[178:181], v[62:65]
	v_mfma_f32_16x16x32_bf16 v[54:57], v[170:173], v[178:181], v[54:57]
	v_mfma_f32_16x16x32_bf16 v[46:49], v[162:165], v[186:189], v[46:49]
	v_mfma_f32_16x16x32_bf16 v[38:41], v[170:173], v[186:189], v[38:41]
	v_mfma_f32_16x16x32_bf16 v[30:33], v[162:165], v[194:197], v[30:33]
	v_mfma_f32_16x16x32_bf16 v[22:25], v[170:173], v[194:197], v[22:25]
	v_mfma_f32_16x16x32_bf16 v[14:17], v[162:165], v[202:205], v[14:17]
	v_mfma_f32_16x16x32_bf16 v[2:5], v[170:173], v[202:205], v[2:5]
	s_barrier
	s_add_i32 s66, s66, 2
	s_add_u32 s64, s64, 0x100
	s_addc_u32 s65, s65, 0
	s_cmp_gt_u32 s66, 13
	s_mov_b64 s[36:37], s[0:1]
	s_cbranch_scc0 .LBB0_1424
	s_and_b64 vcc, exec, s[8:9]
	s_cbranch_vccz .LBB0_1427
	s_barrier
